# six full chunk-prep rounds before the scan (three late rounds on the sample workgroups) and the branch-free step 2 in the late-prep copy as well
# speedup vs baseline: 1.0235x; 1.0031x over previous
; __device__ __forceinline__ int fresh_tid() { int t = threadIdx.x; asm volatile("" : "+v"(t)); return t; }
; __device__ __forceinline__ void gdn_prep_load(PrepRaw& R, int item, int b0, const bf16_t* qkv, const float* bg, int tid) {
;     const int h = item & 7, c = (item >> 3) % NCHUNK, b = b0 + (item >> 3) / NCHUNK;
;     const int tbase = 64 * c - 48, cc = tid & 15, i0 = (tid >> 4) * 2;
; #pragma unroll
;     for (int part = 0; part < 2; ++part)
; #pragma unroll
;         for (int j = 0; j < 5; ++j) { const int t = tbase + i0 - 3 + j;
;             R.x[part][j] = (t >= 0) ? *(const u32x4*)(qkv + (size_t)(b * LP + t) * CONVCH + part * 1024 + h * 128 + 8 * cc) : (u32x4){0u, 0u, 0u, 0u}; }
; __device__ __forceinline__ void gdn_all(LAS unsigned char* lds, const XcdBarrier& xbar, const int G, const int bx, unsigned char* ws, float* out, const bf16_t* qkv, const float* bg, const float* gconv_w, ...
;     const int nfull = NITEM_P / G, nlate = NITEM_P - nfull * G;
;     unsigned* late_cnt = (unsigned*)(ws + WS_CTL) + 8192 + 1024;
;     {
;         { PrepRaw R; if (nfull > 0) gdn_prep_load(R, bx, 0, qkv, bg, fresh_tid());
;           for (int k = 0; k < nfull; ++k) { const int item = bx + k * G; gdn_prep_item(lds, item, 0, R, k + 1 < nfull ? item + G : -1, qkv, bg, gconv_w, gdn_rec(ws, out, item), gtarr); } }
.LBB0_435:
	s_or_b64 exec, exec, s[0:1]
	s_abs_i32 s53, s96
	s_waitcnt lgkmcnt(0)
	v_cvt_f32_u32_e32 v1, s53
	s_sub_i32 s0, 0, s53
	s_barrier
	v_rcp_iflag_f32_e32 v1, v1
	s_nop 0
	v_mul_f32_e32 v1, 0x4f7ffffe, v1
	v_cvt_u32_f32_e32 v1, v1
	s_nop 0
	v_readfirstlane_b32 s56, v1
	s_mul_i32 s0, s0, s56
	s_mul_hi_u32 s0, s56, s0
	s_add_i32 s56, s56, s0
	s_mul_hi_u32 s0, s56, 0x840
	s_mul_i32 s1, s0, s53
	s_sub_i32 s1, 0x840, s1
	s_add_i32 s2, s0, 1
	s_sub_i32 s3, s1, s53
	s_cmp_ge_u32 s1, s53
	s_cselect_b32 s0, s2, s0
	s_cselect_b32 s1, s3, s1
	s_add_i32 s2, s0, 1
	s_cmp_ge_u32 s1, s53
	s_cselect_b32 s0, s2, s0
	v_readlane_b32 s1, v245, 35
	s_xor_b32 s0, s0, s1
	s_sub_i32 s3, s0, s1
	s_mov_b32 s3, 6
	s_cmp_gt_i32 s3, 0
	s_cselect_b64 s[14:15], -1, 0
	s_cmp_lt_i32 s3, 1
	s_cbranch_scc1 .LBB0_461
	s_and_b32 s100, s94, 7
	s_lshr_b32 s101, s94, 3
	s_and_b32 s98, s101, 7
	s_lshr_b32 s101, s101, 3
	s_mul_i32 s98, s98, 33
	s_add_i32 s98, s98, s101
	s_lshl_b32 s98, s98, 3
	s_or_b32 s99, s98, s100
	s_ashr_i32 s0, s99, 3
	s_mul_hi_i32 s1, s0, 0x3e0f83e1
	s_lshr_b32 s4, s1, 31
	s_ashr_i32 s1, s1, 3
	s_add_i32 s18, s1, s4
	s_mul_i32 s1, s18, 33
	v_mov_b32_e32 v1, v0
	s_sub_i32 s0, s0, s1
	s_lshl_b32 s19, s0, 6
	v_ashrrev_i32_e32 v2, 3, v1
	s_and_b32 s2, s99, 7
	v_and_b32_e32 v2, -2, v2
	s_sub_i32 s0, s19, 51
	v_add_u32_e32 v18, s0, v2
	s_lshl_b32 s0, s2, 8
	s_add_u32 s0, s88, s0
	v_lshlrev_b32_e32 v2, 4, v1
	v_mov_b32_e32 v3, 0
	s_addc_u32 s1, s89, 0
	v_and_b32_e32 v2, 0xf0, v2
	v_mov_b32_e32 v4, v3
	v_mov_b32_e32 v5, v3
	s_mulk_i32 s18, 0x810
	v_lshl_add_u64 v[34:35], s[0:1], 0, v[2:3]
	v_mov_b32_e32 v2, v3
	v_mov_b64_e32 v[8:9], v[4:5]
	v_cmp_lt_i32_e32 vcc, -1, v18
	v_add_u32_e32 v26, s18, v18
	v_mov_b64_e32 v[6:7], v[2:3]
	s_and_saveexec_b64 s[0:1], vcc
	s_cbranch_execz .LBB0_438
	s_movk_i32 s4, 0x1800
	v_mad_i64_i32 v[6:7], s[4:5], v26, s4, v[34:35]
	global_load_dwordx4 v[6:9], v[6:7], off

; __device__ __forceinline__ int fresh_tid() { int t = threadIdx.x; asm volatile("" : "+v"(t)); return t; }
; __device__ __forceinline__ void gdn_prep_load(PrepRaw& R, int item, int b0, const bf16_t* qkv, const float* bg, int tid) {
;     const int h = item & 7, c = (item >> 3) % NCHUNK, b = b0 + (item >> 3) / NCHUNK;
;     const int tbase = 64 * c - 48, cc = tid & 15, i0 = (tid >> 4) * 2;
; #pragma unroll
;     for (int part = 0; part < 2; ++part)
; #pragma unroll
;         for (int j = 0; j < 5; ++j) { const int t = tbase + i0 - 3 + j;
;             R.x[part][j] = (t >= 0) ? *(const u32x4*)(qkv + (size_t)(b * LP + t) * CONVCH + part * 1024 + h * 128 + 8 * cc) : (u32x4){0u, 0u, 0u, 0u}; }
; __device__ __forceinline__ void gdn_all(LAS unsigned char* lds, const XcdBarrier& xbar, const int G, const int bx, unsigned char* ws, float* out, const bf16_t* qkv, const float* bg, const float* gconv_w, ...
;     ...
;     if (nlate > 0 && bx >= G - nlate) {
;         const int item = nfull * G + (bx - (G - nlate)); PrepRaw R; gdn_prep_load(R, item, 0, qkv, bg, fresh_tid());
;         gdn_prep_item(lds, item, 0, R, -1, qkv, bg, gconv_w, gdn_rec(ws, out, item), gtarr);
.Llt_loop:
	s_mul_i32 s18, s99, 0xc0
	s_add_i32 s18, s18, s94
	s_addk_i32 s18, 0x5c0
	s_cmpk_ge_u32 s18, 0x840
	s_cbranch_scc1 .LBB0_704
	s_and_b32 s100, s18, 7
	s_lshr_b32 s101, s18, 3
	s_and_b32 s98, s101, 7
	s_lshr_b32 s101, s101, 3
	s_mul_i32 s98, s98, 33
	s_add_i32 s98, s98, s101
	s_lshl_b32 s98, s98, 3
	s_or_b32 s18, s98, s100
	s_ashr_i32 s0, s18, 3
	s_mul_hi_i32 s1, s0, 0x3e0f83e1
	s_lshr_b32 s4, s1, 31
	s_ashr_i32 s1, s1, 3
	s_add_i32 s19, s1, s4
	s_mul_i32 s1, s19, 33
	v_mov_b32_e32 v1, v0
	s_sub_i32 s0, s0, s1
	s_and_b32 s23, s18, 7
	s_lshl_b32 s24, s0, 6
	s_waitcnt vmcnt(0)
	v_ashrrev_i32_e32 v2, 3, v1
	v_and_b32_e32 v2, -2, v2
	s_sub_i32 s22, s24, 51
	s_lshl_b32 s0, s23, 8
	v_add_u32_e32 v8, s22, v2
	s_add_u32 s0, s88, s0
	v_lshlrev_b32_e32 v2, 4, v1
	s_mulk_i32 s19, 0x810
	s_addc_u32 s1, s89, 0
	v_and_b32_e32 v90, 0xf0, v2
	v_mov_b32_e32 v91, 0
	v_lshl_add_u64 v[2:3], s[0:1], 0, v[90:91]
	v_cmp_lt_i32_e32 vcc, -1, v8
	v_add_u32_e32 v4, s19, v8
	v_mov_b32_e32 v42, 0
	v_mov_b32_e32 v43, 0
	v_mov_b32_e32 v44, 0
	v_mov_b32_e32 v45, 0
	s_and_saveexec_b64 s[0:1], vcc
	s_cbranch_execz .LBB0_616
	s_movk_i32 s4, 0x1800
	v_mad_i64_i32 v[6:7], s[4:5], v4, s4, v[2:3]
	global_load_dwordx4 v[42:45], v[6:7], off

; __device__ __forceinline__ float silu_f(float x) { return x * __builtin_amdgcn_rcpf(1.0f + __expf(-x)); }
; __device__ __forceinline__ void gdn_prep_item(LAS unsigned char* lds, int item, int b0, PrepRaw& R, int next_item, const bf16_t* qkv, const float* bg, const float* gconv_w, unsigned char* rec, float* gtarr) {
;     ...
;     {
;         const int cc = tid & 15, i0 = (tid >> 4) * 2;
;         const float be0 = Bs[i0], be1 = Bs[i0 + 1], eg0 = EG[i0], eg1 = EG[i0 + 1];
; #pragma unroll
;         for (int part = 0; part < 3; ++part) {
;             const int col = part * 1024 + h * 128 + 8 * cc;
;             float y0[8], y1[8];
; #pragma unroll
;             for (int e = 0; e < 8; ++e) { y0[e] = 0.f; y1[e] = 0.f; }
; #pragma unroll
;             for (int j = 0; j < 5; ++j) { const u32x4 v = part < 2 ? R.x[part < 2 ? part : 0][j] : xv[j]; const unsigned vv[4] = {v.x, v.y, v.z, v.w}; float x[8];
; #pragma unroll
;                 for (int e = 0; e < 4; ++e) { x[2 * e] = __uint_as_float(vv[e] << 16); x[2 * e + 1] = __uint_as_float(vv[e] & 0xffff0000u); }
;                 if (j < 4) { const f32x4 wa = *(const f32x4*)(gconv_w + j * CONVCH + col), wb = *(const f32x4*)(gconv_w + j * CONVCH + col + 4);
; #pragma unroll
;                     for (int e = 0; e < 8; ++e) y0[e] += (e < 4 ? wa[e] : wb[e - 4]) * x[e]; }
;                 if (j > 0) { const f32x4 wa = *(const f32x4*)(gconv_w + (j - 1) * CONVCH + col), wb = *(const f32x4*)(gconv_w + (j - 1) * CONVCH + col + 4);
; #pragma unroll
;                     for (int e = 0; e < 8; ++e) y1[e] += (e < 4 ? wa[e] : wb[e - 4]) * x[e]; } }
;             float s0 = 0.f, s1 = 0.f;
; #pragma unroll
;             for (int e = 0; e < 8; ++e) { y0[e] = silu_f(y0[e]); y1[e] = silu_f(y1[e]); s0 += y0[e] * y0[e]; s1 += y1[e] * y1[e]; }
.LBB0_655:
	s_or_b64 exec, exec, s[0:1]
	s_waitcnt vmcnt(0)
	v_or_b32_e32 v58, s6, v90
	v_lshlrev_b32_e32 v86, 2, v58
	v_mov_b32_e32 v87, 0
	s_waitcnt lgkmcnt(0)
	s_barrier
	v_lshl_add_u64 v[88:89], s[72:73], 0, v[86:87]
	global_load_dwordx4 v[78:81], v86, s[72:73] offset:16
	s_mov_b64 s[0:1], 0x3000
	v_lshl_add_u64 v[62:63], v[88:89], 0, s[0:1]
	s_mov_b64 s[0:1], 0x6000
	v_lshl_add_u64 v[64:65], v[88:89], 0, s[0:1]
	global_load_dwordx4 v[82:85], v[62:63], off offset:16
	global_load_dwordx4 v[104:107], v[64:65], off offset:16
	s_mov_b64 s[0:1], 0x9000
	v_lshl_add_u64 v[62:63], v[88:89], 0, s[0:1]
	global_load_dwordx4 v[108:111], v[62:63], off offset:16
	s_nop 0
	global_load_dwordx4 v[62:65], v86, s[72:73]
	s_movk_i32 s0, 0x4000
	v_add_co_u32_e32 v94, vcc, s0, v88
	s_movk_i32 s1, 0x7000
	s_nop 0
	v_addc_co_u32_e32 v95, vcc, 0, v89, vcc
	v_add_co_u32_e32 v96, vcc, s1, v88
	s_mov_b32 s4, 0xa000
	s_nop 0
	v_addc_co_u32_e32 v97, vcc, 0, v89, vcc
	v_add_co_u32_e32 v92, vcc, s4, v88
	global_load_dwordx4 v[66:69], v[94:95], off offset:-4096
	global_load_dwordx4 v[70:73], v[96:97], off offset:-4096
	v_addc_co_u32_e32 v93, vcc, 0, v89, vcc
	global_load_dwordx4 v[74:77], v[92:93], off offset:-4096
	v_or_b32_e32 v103, 1, v98
	v_lshlrev_b32_e32 v58, 2, v102
	s_add_i32 s0, 0, 0x1d100
	s_add_i32 s21, 0, 0x1d200
	v_lshlrev_b32_e32 v112, 16, v61
	v_and_b32_e32 v113, 0xffff0000, v61
	v_lshlrev_b32_e32 v120, 16, v60
	v_and_b32_e32 v121, 0xffff0000, v60
	v_lshlrev_b32_e32 v122, 16, v52
	v_and_b32_e32 v123, 0xffff0000, v52
	v_lshlrev_b32_e32 v52, 2, v103
	v_lshlrev_b32_e32 v114, 16, v53
	v_and_b32_e32 v115, 0xffff0000, v53
	v_lshlrev_b32_e32 v116, 16, v49
	v_and_b32_e32 v117, 0xffff0000, v49
	v_lshlrev_b32_e32 v118, 16, v57
	v_and_b32_e32 v119, 0xffff0000, v57
	v_lshlrev_b32_e32 v124, 16, v48
	v_and_b32_e32 v125, 0xffff0000, v48
	v_lshlrev_b32_e32 v48, 16, v56
	v_and_b32_e32 v49, 0xffff0000, v56
	v_lshlrev_b32_e32 v56, 16, v59
	v_and_b32_e32 v57, 0xffff0000, v59
	v_add_u32_e32 v60, s0, v58
	v_add_u32_e32 v61, s21, v58
	v_add_u32_e32 v128, s0, v52
	v_add_u32_e32 v129, s21, v52
	v_lshlrev_b32_e32 v130, 16, v47
	v_and_b32_e32 v131, 0xffff0000, v47
	v_lshlrev_b32_e32 v132, 16, v55
	v_and_b32_e32 v133, 0xffff0000, v55
	v_lshlrev_b32_e32 v136, 16, v91
	v_and_b32_e32 v137, 0xffff0000, v91
	v_lshlrev_b32_e32 v140, 16, v50
	v_and_b32_e32 v141, 0xffff0000, v50
	s_movk_i32 s1, 0x88
	s_mov_b32 s0, 0x358637bd
	s_mov_b32 s4, 0x800000
	v_lshrrev_b32_e32 v86, 4, v101
	s_waitcnt vmcnt(7)
	v_pk_fma_f32 v[52:53], v[80:81], v[112:113], 0 op_sel_hi:[1,1,0]
	v_pk_fma_f32 v[58:59], v[78:79], v[120:121], 0 op_sel_hi:[1,1,0]
	s_waitcnt vmcnt(6)
	v_pk_fma_f32 v[52:53], v[84:85], v[114:115], v[52:53]
	v_pk_fma_f32 v[58:59], v[82:83], v[122:123], v[58:59]
	s_waitcnt vmcnt(5)
	v_pk_fma_f32 v[52:53], v[106:107], v[116:117], v[52:53]
	v_pk_fma_f32 v[58:59], v[104:105], v[124:125], v[58:59]
	s_waitcnt vmcnt(4)
	v_pk_fma_f32 v[52:53], v[110:111], v[118:119], v[52:53]
	v_pk_fma_f32 v[118:119], v[108:109], v[48:49], v[58:59]
	v_mul_f32_e32 v48, 0xbfb8aa3b, v52
	v_mul_f32_e32 v49, 0xbfb8aa3b, v53
	v_mul_f32_e32 v58, 0xbfb8aa3b, v118
	v_mul_f32_e32 v59, 0xbfb8aa3b, v119
	v_exp_f32_e32 v48, v48
	v_exp_f32_e32 v49, v49
	v_exp_f32_e32 v58, v58
	v_exp_f32_e32 v59, v59
	v_add_f32_e32 v48, 1.0, v48
	v_add_f32_e32 v49, 1.0, v49
	v_add_f32_e32 v58, 1.0, v58
	v_add_f32_e32 v59, 1.0, v59
	v_rcp_f32_e32 v48, v48
	v_rcp_f32_e32 v49, v49
	v_rcp_f32_e32 v126, v58
	v_rcp_f32_e32 v127, v59
	ds_read_b32 v58, v60
	ds_read_b32 v59, v128
	ds_read_b32 v60, v61
	ds_read_b32 v61, v129
	v_pk_mul_f32 v[48:49], v[52:53], v[48:49]
	v_lshlrev_b32_e32 v128, 16, v51
	v_pk_mul_f32 v[52:53], v[118:119], v[126:127]
	s_waitcnt vmcnt(3)
	v_pk_fma_f32 v[126:127], v[64:65], v[56:57], 0 op_sel_hi:[1,1,0]
	v_and_b32_e32 v129, 0xffff0000, v51
	s_waitcnt vmcnt(2)
	v_pk_fma_f32 v[126:127], v[68:69], v[128:129], v[126:127]
	v_pk_fma_f32 v[138:139], v[62:63], v[136:137], 0 op_sel_hi:[1,1,0]
	s_waitcnt vmcnt(1)
	v_pk_fma_f32 v[126:127], v[72:73], v[130:131], v[126:127]
	v_pk_mul_f32 v[118:119], v[48:49], v[48:49]
	s_waitcnt vmcnt(0)
	v_pk_fma_f32 v[126:127], v[76:77], v[132:133], v[126:127]
	v_pk_mul_f32 v[132:133], v[52:53], v[52:53]
	v_mul_f32_e32 v47, 0xbfb8aa3b, v126
	v_exp_f32_e32 v47, v47
	v_mul_f32_e32 v51, 0xbfb8aa3b, v127
	v_exp_f32_e32 v51, v51
	v_add_f32_e32 v47, 1.0, v47
	v_rcp_f32_e32 v134, v47
	v_add_f32_e32 v47, 1.0, v51
	v_pk_fma_f32 v[50:51], v[66:67], v[140:141], v[138:139]
	v_lshlrev_b32_e32 v138, 16, v46
	v_and_b32_e32 v139, 0xffff0000, v46
	v_rcp_f32_e32 v135, v47
	v_pk_fma_f32 v[46:47], v[70:71], v[138:139], v[50:51]
	v_lshlrev_b32_e32 v50, 16, v54
	v_and_b32_e32 v51, 0xffff0000, v54
	v_pk_fma_f32 v[46:47], v[74:75], v[50:51], v[46:47]
	s_nop 0
	v_mul_f32_e32 v50, 0xbfb8aa3b, v46
	v_exp_f32_e32 v54, v50
	v_mul_f32_e32 v50, 0xbfb8aa3b, v47
	v_exp_f32_e32 v55, v50
	v_pk_mul_f32 v[50:51], v[126:127], v[134:135]
	v_lshlrev_b32_e32 v126, 16, v45
	v_and_b32_e32 v127, 0xffff0000, v45
	v_pk_fma_f32 v[80:81], v[80:81], v[126:127], 0 op_sel_hi:[1,1,0]
	v_add_f32_e32 v54, 1.0, v54
	v_pk_fma_f32 v[80:81], v[84:85], v[112:113], v[80:81]
	v_add_f32_e32 v55, 1.0, v55
	v_pk_fma_f32 v[80:81], v[106:107], v[114:115], v[80:81]
	v_rcp_f32_e32 v54, v54
	v_pk_fma_f32 v[80:81], v[110:111], v[116:117], v[80:81]
	v_rcp_f32_e32 v55, v55
	v_mul_f32_e32 v45, 0xbfb8aa3b, v80
	v_exp_f32_e32 v45, v45
	v_mul_f32_e32 v84, 0xbfb8aa3b, v81
	v_exp_f32_e32 v85, v84
	v_pk_mul_f32 v[46:47], v[46:47], v[54:55]
	v_add_f32_e32 v45, 1.0, v45
	v_rcp_f32_e32 v84, v45
	v_add_f32_e32 v45, 1.0, v85
	v_rcp_f32_e32 v85, v45
	v_pk_mul_f32 v[54:55], v[46:47], v[46:47]
; #define LAS __attribute__((address_space(3)))
; __device__ __forceinline__ unsigned cvt_pk_bf16(float lo, float hi) { const bf16x2_t r = __builtin_convertvector((f32x2){lo, hi}, bf16x2_t); return __builtin_bit_cast(unsigned, r); }
; __device__ __forceinline__ float silu_f(float x) { return x * __builtin_amdgcn_rcpf(1.0f + __expf(-x)); }
; __device__ __forceinline__ void gdn_prep_item(LAS unsigned char* lds, int item, int b0, PrepRaw& R, int next_item, const bf16_t* qkv, const float* bg, const float* gconv_w, unsigned char* rec, float* gtarr) {
;     ...
;             float s0 = 0.f, s1 = 0.f;
; #pragma unroll
;             for (int e = 0; e < 8; ++e) { y0[e] = silu_f(y0[e]); y1[e] = silu_f(y1[e]); s0 += y0[e] * y0[e]; s1 += y1[e] * y1[e]; }
;             if (part < 2) {
;                 s0 = row16_sum(s0); s1 = row16_sum(s1);
;                 float sc0 = rsqrtf(s0 + EPS), sc1 = rsqrtf(s1 + EPS); if (part == 0) { sc0 *= 0.08838834764831845f; sc1 *= 0.08838834764831845f; }
; #pragma unroll
;                 for (int e = 0; e < 8; ++e) { y0[e] *= sc0; y1[e] *= sc1; }
;                 LAS unsigned char* img = lds + (part == 0 ? P2_QN : P2_KN);
;                 u32x4 w0, w1; w0.x = cvt_pk_bf16(y0[0], y0[1]); w0.y = cvt_pk_bf16(y0[2], y0[3]); w0.z = cvt_pk_bf16(y0[4], y0[5]); w0.w = cvt_pk_bf16(y0[6], y0[7]);
;                 w1.x = cvt_pk_bf16(y1[0], y1[1]); w1.y = cvt_pk_bf16(y1[2], y1[3]); w1.z = cvt_pk_bf16(y1[4], y1[5]); w1.w = cvt_pk_bf16(y1[6], y1[7]);
;                 *(LAS u32x4*)(img + (i0 * 136 + 8 * cc) * 2) = w0; *(LAS u32x4*)(img + ((i0 + 1) * 136 + 8 * cc) * 2) = w1;
	v_pk_mul_f32 v[106:107], v[50:51], v[50:51]
	v_pk_mul_f32 v[80:81], v[80:81], v[84:85]
	v_lshlrev_b32_e32 v84, 16, v44
	v_and_b32_e32 v85, 0xffff0000, v44
	v_pk_fma_f32 v[44:45], v[78:79], v[84:85], 0 op_sel_hi:[1,1,0]
	v_lshlrev_b32_e32 v84, 16, v43
	v_and_b32_e32 v85, 0xffff0000, v43
	v_pk_fma_f32 v[64:65], v[64:65], v[84:85], 0 op_sel_hi:[1,1,0]
	v_pk_fma_f32 v[44:45], v[82:83], v[120:121], v[44:45]
	v_pk_fma_f32 v[56:57], v[68:69], v[56:57], v[64:65]
	v_lshlrev_b32_e32 v68, 16, v42
	v_pk_fma_f32 v[56:57], v[72:73], v[128:129], v[56:57]
	v_and_b32_e32 v69, 0xffff0000, v42
	v_pk_fma_f32 v[56:57], v[76:77], v[130:131], v[56:57]
	v_pk_fma_f32 v[44:45], v[104:105], v[122:123], v[44:45]
	v_mul_f32_e32 v43, 0xbfb8aa3b, v56
	v_exp_f32_e32 v43, v43
	v_mul_f32_e32 v64, 0xbfb8aa3b, v57
	v_exp_f32_e32 v65, v64
	v_pk_fma_f32 v[44:45], v[108:109], v[124:125], v[44:45]
	v_add_f32_e32 v43, 1.0, v43
	v_rcp_f32_e32 v64, v43
	v_pk_fma_f32 v[42:43], v[62:63], v[68:69], 0 op_sel_hi:[1,1,0]
	v_mul_f32_e32 v78, 0xbfb8aa3b, v44
	v_pk_fma_f32 v[42:43], v[66:67], v[136:137], v[42:43]
	v_exp_f32_e32 v82, v78
	v_pk_fma_f32 v[42:43], v[70:71], v[140:141], v[42:43]
	v_mul_f32_e32 v78, 0xbfb8aa3b, v45
	v_pk_fma_f32 v[42:43], v[74:75], v[138:139], v[42:43]
	v_exp_f32_e32 v83, v78
	v_mul_f32_e32 v62, 0xbfb8aa3b, v42
	v_mul_f32_e32 v63, 0xbfb8aa3b, v43
	v_exp_f32_e32 v62, v62
	v_exp_f32_e32 v63, v63
	v_add_f32_e32 v65, 1.0, v65
	v_rcp_f32_e32 v65, v65
	v_add_f32_e32 v62, 1.0, v62
	v_add_f32_e32 v63, 1.0, v63
	v_rcp_f32_e32 v62, v62
	v_rcp_f32_e32 v63, v63
	v_add_f32_e32 v82, 1.0, v82
	v_add_f32_e32 v83, 1.0, v83
	v_rcp_f32_e32 v82, v82
	v_rcp_f32_e32 v83, v83
	v_pk_mul_f32 v[42:43], v[42:43], v[62:63]
	v_pk_mul_f32 v[56:57], v[56:57], v[64:65]
	v_pk_mul_f32 v[62:63], v[42:43], v[42:43]
	v_pk_mul_f32 v[64:65], v[56:57], v[56:57]
	v_mov_b32_e32 v68, v54
	v_mov_b32_e32 v69, v62
	v_mov_b32_e32 v62, v55
	v_pk_mul_f32 v[44:45], v[44:45], v[82:83]
	v_pk_add_f32 v[54:55], v[68:69], v[62:63]
	v_mov_b32_e32 v62, v106
	v_mov_b32_e32 v63, v64
	v_pk_mul_f32 v[66:67], v[44:45], v[44:45]
	v_pk_add_f32 v[54:55], v[62:63], v[54:55]
	v_mov_b32_e32 v64, v107
	v_pk_add_f32 v[54:55], v[64:65], v[54:55]
	v_mov_b32_e32 v62, v132
	v_mov_b32_e32 v63, v66
	v_pk_mul_f32 v[78:79], v[80:81], v[80:81]
	v_pk_add_f32 v[54:55], v[62:63], v[54:55]
	v_mov_b32_e32 v66, v133
	v_pk_add_f32 v[54:55], v[66:67], v[54:55]
	v_mov_b32_e32 v62, v118
	v_mov_b32_e32 v63, v78
	v_pk_add_f32 v[54:55], v[62:63], v[54:55]
	v_mov_b32_e32 v78, v119
	v_pk_add_f32 v[54:55], v[78:79], v[54:55]
	v_mov_b32_e32 v62, v87
	v_mov_b32_e32 v63, v87
	v_mad_u64_u32 v[64:65], s[6:7], v103, s1, v[90:91]
	v_mov_b32_dpp v62, v54 quad_perm:[1,0,3,2] row_mask:0xf bank_mask:0xf
	v_mov_b32_dpp v63, v55 quad_perm:[1,0,3,2] row_mask:0xf bank_mask:0xf
	v_pk_add_f32 v[54:55], v[54:55], v[62:63]
	v_mov_b32_e32 v62, v87
	v_mov_b32_e32 v63, v87
	v_lshl_add_u32 v116, v64, 1, 0
	v_mov_b32_dpp v62, v54 quad_perm:[2,3,0,1] row_mask:0xf bank_mask:0xf
	v_mov_b32_dpp v63, v55 quad_perm:[2,3,0,1] row_mask:0xf bank_mask:0xf
	v_pk_add_f32 v[54:55], v[54:55], v[62:63]
	v_mov_b32_e32 v62, v87
	v_mov_b32_e32 v63, v87
	s_nop 0
	v_mov_b32_dpp v62, v54 row_ror:4 row_mask:0xf bank_mask:0xf
	v_mov_b32_dpp v63, v55 row_ror:4 row_mask:0xf bank_mask:0xf
	v_pk_add_f32 v[54:55], v[54:55], v[62:63]
	v_mov_b32_e32 v62, v87
	v_mov_b32_e32 v63, v87
	s_nop 0
	v_mov_b32_dpp v62, v54 row_ror:8 row_mask:0xf bank_mask:0xf
	v_mov_b32_dpp v63, v55 row_ror:8 row_mask:0xf bank_mask:0xf
	v_pk_add_f32 v[54:55], v[54:55], v[62:63]
	s_nop 0
	v_pk_add_f32 v[54:55], v[54:55], s[0:1] op_sel_hi:[1,0]
	s_nop 0
	v_mul_f32_e32 v62, 0x4b800000, v54
	v_cmp_gt_f32_e32 vcc, s4, v54
	s_nop 1
	v_cndmask_b32_e32 v54, v54, v62, vcc
	v_rsq_f32_e32 v54, v54
	v_mad_u64_u32 v[62:63], s[6:7], v102, s1, v[90:91]
	v_lshl_add_u32 v103, v62, 1, 0
	v_mul_f32_e32 v63, 0x45800000, v54
	v_cndmask_b32_e32 v54, v54, v63, vcc
	v_mul_f32_e32 v54, 0x3db504f3, v54
	v_mul_f32_e32 v63, 0x4b800000, v55
	v_cmp_gt_f32_e32 vcc, s4, v55
	v_pk_mul_f32 v[46:47], v[46:47], v[54:55] op_sel_hi:[1,0]
	s_nop 0
	v_cndmask_b32_e32 v55, v55, v63, vcc
	v_rsq_f32_e32 v63, v55
	v_pk_mul_f32 v[50:51], v[50:51], v[54:55] op_sel_hi:[1,0]
	v_pk_mul_f32 v[52:53], v[52:53], v[54:55] op_sel_hi:[1,0]
	v_pk_mul_f32 v[54:55], v[48:49], v[54:55] op_sel_hi:[1,0]
	v_mul_f32_e32 v48, 0x45800000, v63
	v_cndmask_b32_e32 v48, v63, v48, vcc
	v_mul_f32_e32 v48, 0x3db504f3, v48
	v_pk_mul_f32 v[42:43], v[42:43], v[48:49] op_sel_hi:[1,0]
	v_pk_mul_f32 v[56:57], v[56:57], v[48:49] op_sel_hi:[1,0]
	v_pk_mul_f32 v[44:45], v[44:45], v[48:49] op_sel_hi:[1,0]
	v_pk_mul_f32 v[48:49], v[80:81], v[48:49] op_sel_hi:[1,0]
	v_cvt_pk_bf16_f32 v42, v42, v43
	v_cvt_pk_bf16_f32 v43, v56, v57
	v_cvt_pk_bf16_f32 v44, v44, v45
	v_cvt_pk_bf16_f32 v45, v48, v49
	v_cvt_pk_bf16_f32 v46, v46, v47
	v_cvt_pk_bf16_f32 v47, v50, v51
	v_cvt_pk_bf16_f32 v48, v52, v53
	v_cvt_pk_bf16_f32 v49, v54, v55
	ds_write_b128 v103, v[42:45]
	ds_write_b128 v116, v[46:49]
	s_movk_i32 s5, 0x2000
	s_mov_b64 s[6:7], 0x1000
	v_add_co_u32_e32 v62, vcc, s5, v88
	v_lshl_add_u64 v[46:47], v[88:89], 0, s[6:7]
	s_nop 0
	v_addc_co_u32_e32 v63, vcc, 0, v89, vcc
	s_mov_b64 s[6:7], 0x4000
	global_load_dwordx4 v[42:45], v[62:63], off offset:-4096
	global_load_dwordx4 v[64:67], v[46:47], off offset:16
	v_lshl_add_u64 v[46:47], v[88:89], 0, s[6:7]
	global_load_dwordx4 v[68:71], v[46:47], off offset:16
	s_mov_b64 s[6:7], 0x7000
	v_lshl_add_u64 v[54:55], v[88:89], 0, s[6:7]
	global_load_dwordx4 v[46:49], v[94:95], off
	global_load_dwordx4 v[50:53], v[96:97], off
	global_load_dwordx4 v[72:75], v[54:55], off offset:16
	s_mov_b64 s[6:7], 0xa000
	v_lshl_add_u64 v[54:55], v[88:89], 0, s[6:7]
	global_load_dwordx4 v[76:79], v[54:55], off offset:16
	s_nop 0
	global_load_dwordx4 v[54:57], v[92:93], off
	v_lshlrev_b32_e32 v92, 16, v36
	v_and_b32_e32 v93, 0xffff0000, v36
	v_lshlrev_b32_e32 v80, 16, v37
	v_and_b32_e32 v81, 0xffff0000, v37
	v_lshlrev_b32_e32 v82, 16, v29
	v_and_b32_e32 v83, 0xffff0000, v29
	v_lshlrev_b32_e32 v84, 16, v41
	v_and_b32_e32 v85, 0xffff0000, v41
	v_lshlrev_b32_e32 v90, 16, v33
	v_and_b32_e32 v91, 0xffff0000, v33
	v_lshlrev_b32_e32 v36, 16, v28
	v_and_b32_e32 v37, 0xffff0000, v28
	v_lshlrev_b32_e32 v28, 16, v40
	v_and_b32_e32 v29, 0xffff0000, v40
	v_lshlrev_b32_e32 v40, 16, v32
	v_and_b32_e32 v41, 0xffff0000, v32
	v_lshlrev_b32_e32 v32, 16, v35
	v_and_b32_e32 v33, 0xffff0000, v35
	v_lshlrev_b32_e32 v94, 16, v27
	v_and_b32_e32 v95, 0xffff0000, v27
	v_lshlrev_b32_e32 v96, 16, v39
	v_and_b32_e32 v97, 0xffff0000, v39
	v_lshlrev_b32_e32 v106, 16, v34
	v_and_b32_e32 v107, 0xffff0000, v34
	v_lshlrev_b32_e32 v34, 16, v26
	v_and_b32_e32 v35, 0xffff0000, v26
	v_lshlrev_b32_e32 v26, 16, v38
	v_and_b32_e32 v27, 0xffff0000, v38
	v_lshlrev_b32_e32 v104, 16, v31
	v_and_b32_e32 v105, 0xffff0000, v31
	s_waitcnt vmcnt(7)
; __device__ __forceinline__ float silu_f(float x) { return x * __builtin_amdgcn_rcpf(1.0f + __expf(-x)); }
; __device__ __forceinline__ void gdn_prep_item(LAS unsigned char* lds, int item, int b0, PrepRaw& R, int next_item, const bf16_t* qkv, const float* bg, const float* gconv_w, unsigned char* rec, float* gtarr) {
;     ...
;             for (int j = 0; j < 5; ++j) { const u32x4 v = part < 2 ? R.x[part < 2 ? part : 0][j] : xv[j]; const unsigned vv[4] = {v.x, v.y, v.z, v.w}; float x[8];
; #pragma unroll
;                 for (int e = 0; e < 4; ++e) { x[2 * e] = __uint_as_float(vv[e] << 16); x[2 * e + 1] = __uint_as_float(vv[e] & 0xffff0000u); }
;                 if (j < 4) { const f32x4 wa = *(const f32x4*)(gconv_w + j * CONVCH + col), wb = *(const f32x4*)(gconv_w + j * CONVCH + col + 4);
; #pragma unroll
;                     for (int e = 0; e < 8; ++e) y0[e] += (e < 4 ? wa[e] : wb[e - 4]) * x[e]; }
;                 if (j > 0) { const f32x4 wa = *(const f32x4*)(gconv_w + (j - 1) * CONVCH + col), wb = *(const f32x4*)(gconv_w + (j - 1) * CONVCH + col + 4);
; #pragma unroll
;                     for (int e = 0; e < 8; ++e) y1[e] += (e < 4 ? wa[e] : wb[e - 4]) * x[e]; } }
;             float s0 = 0.f, s1 = 0.f;
; #pragma unroll
;             for (int e = 0; e < 8; ++e) { y0[e] = silu_f(y0[e]); y1[e] = silu_f(y1[e]); s0 += y0[e] * y0[e]; s1 += y1[e] * y1[e]; }
	v_pk_fma_f32 v[110:111], v[44:45], v[32:33], 0 op_sel_hi:[1,1,0]
	s_waitcnt vmcnt(6)
	v_pk_fma_f32 v[108:109], v[64:65], v[92:93], 0 op_sel_hi:[1,1,0]
	v_pk_fma_f32 v[38:39], v[66:67], v[80:81], 0 op_sel_hi:[1,1,0]
	s_waitcnt vmcnt(5)
	v_pk_fma_f32 v[108:109], v[68:69], v[36:37], v[108:109]
	v_pk_fma_f32 v[38:39], v[70:71], v[82:83], v[38:39]
	s_waitcnt vmcnt(4)
	v_pk_fma_f32 v[110:111], v[48:49], v[94:95], v[110:111]
	s_waitcnt vmcnt(2)
	v_pk_fma_f32 v[108:109], v[72:73], v[28:29], v[108:109]
	v_pk_fma_f32 v[38:39], v[74:75], v[84:85], v[38:39]
	v_pk_fma_f32 v[110:111], v[52:53], v[96:97], v[110:111]
	s_waitcnt vmcnt(1)
	v_pk_fma_f32 v[40:41], v[76:77], v[40:41], v[108:109]
	v_pk_fma_f32 v[38:39], v[78:79], v[90:91], v[38:39]
	s_waitcnt vmcnt(0)
	v_pk_fma_f32 v[90:91], v[56:57], v[104:105], v[110:111]
	v_mul_f32_e32 v105, 0xbfb8aa3b, v40
	v_mul_f32_e32 v108, 0xbfb8aa3b, v41
	v_mul_f32_e32 v31, 0xbfb8aa3b, v38
	v_mul_f32_e32 v109, 0xbfb8aa3b, v90
	v_exp_f32_e32 v105, v105
	v_exp_f32_e32 v108, v108
	v_mul_f32_e32 v104, 0xbfb8aa3b, v39
	v_exp_f32_e32 v31, v31
	v_exp_f32_e32 v109, v109
	v_mul_f32_e32 v110, 0xbfb8aa3b, v91
	v_exp_f32_e32 v104, v104
	v_pk_fma_f32 v[112:113], v[42:43], v[106:107], 0 op_sel_hi:[1,1,0]
	v_exp_f32_e32 v110, v110
	v_pk_fma_f32 v[112:113], v[46:47], v[34:35], v[112:113]
	v_add_f32_e32 v114, 1.0, v105
	v_add_f32_e32 v115, 1.0, v108
	v_pk_fma_f32 v[112:113], v[50:51], v[26:27], v[112:113]
	v_add_f32_e32 v31, 1.0, v31
	v_add_f32_e32 v117, 1.0, v109
	v_rcp_f32_e32 v108, v114
	v_rcp_f32_e32 v109, v115
	v_lshlrev_b32_e32 v114, 16, v30
	v_and_b32_e32 v115, 0xffff0000, v30
	v_add_f32_e32 v111, 1.0, v104
	v_rcp_f32_e32 v104, v31
	v_pk_fma_f32 v[30:31], v[54:55], v[114:115], v[112:113]
	v_add_f32_e32 v118, 1.0, v110
	v_mul_f32_e32 v112, 0xbfb8aa3b, v30
	v_mul_f32_e32 v113, 0xbfb8aa3b, v31
	v_rcp_f32_e32 v105, v111
	v_rcp_f32_e32 v110, v117
	v_rcp_f32_e32 v111, v118
	v_exp_f32_e32 v112, v112
	v_exp_f32_e32 v113, v113
	v_pk_mul_f32 v[40:41], v[40:41], v[108:109]
	v_pk_mul_f32 v[90:91], v[90:91], v[110:111]
	v_add_f32_e32 v110, 1.0, v112
	v_add_f32_e32 v111, 1.0, v113
	v_lshlrev_b32_e32 v112, 16, v25
	v_and_b32_e32 v113, 0xffff0000, v25
	v_pk_fma_f32 v[66:67], v[66:67], v[112:113], 0 op_sel_hi:[1,1,0]
	v_rcp_f32_e32 v110, v110
	v_pk_fma_f32 v[66:67], v[70:71], v[80:81], v[66:67]
	v_rcp_f32_e32 v111, v111
	v_pk_fma_f32 v[66:67], v[74:75], v[82:83], v[66:67]
	v_pk_mul_f32 v[74:75], v[90:91], v[90:91]
	v_pk_fma_f32 v[66:67], v[78:79], v[84:85], v[66:67]
	v_pk_mul_f32 v[30:31], v[30:31], v[110:111]
	v_mul_f32_e32 v25, 0xbfb8aa3b, v66
	v_exp_f32_e32 v25, v25
	v_mul_f32_e32 v70, 0xbfb8aa3b, v67
	v_exp_f32_e32 v71, v70
	v_pk_mul_f32 v[78:79], v[30:31], v[30:31]
	v_add_f32_e32 v25, 1.0, v25
	v_rcp_f32_e32 v70, v25
	v_add_f32_e32 v25, 1.0, v71
	v_rcp_f32_e32 v71, v25
	v_pk_mul_f32 v[108:109], v[40:41], v[40:41]
	v_pk_mul_f32 v[38:39], v[38:39], v[104:105]
	v_pk_mul_f32 v[66:67], v[66:67], v[70:71]
	v_lshlrev_b32_e32 v70, 16, v24
	v_and_b32_e32 v71, 0xffff0000, v24
	v_pk_fma_f32 v[24:25], v[64:65], v[70:71], 0 op_sel_hi:[1,1,0]
	v_lshlrev_b32_e32 v64, 16, v23
	v_pk_fma_f32 v[24:25], v[68:69], v[92:93], v[24:25]
	v_and_b32_e32 v65, 0xffff0000, v23
	v_pk_fma_f32 v[24:25], v[72:73], v[36:37], v[24:25]
	v_pk_fma_f32 v[44:45], v[44:45], v[64:65], 0 op_sel_hi:[1,1,0]
	v_pk_fma_f32 v[24:25], v[76:77], v[28:29], v[24:25]
	v_pk_fma_f32 v[32:33], v[48:49], v[32:33], v[44:45]
	v_mul_f32_e32 v28, 0xbfb8aa3b, v24
	v_exp_f32_e32 v36, v28
	v_mul_f32_e32 v28, 0xbfb8aa3b, v25
	v_exp_f32_e32 v37, v28
	v_pk_fma_f32 v[32:33], v[52:53], v[94:95], v[32:33]
	v_add_f32_e32 v36, 1.0, v36
	v_pk_fma_f32 v[32:33], v[56:57], v[96:97], v[32:33]
	v_add_f32_e32 v37, 1.0, v37
	v_mul_f32_e32 v23, 0xbfb8aa3b, v32
	v_mul_f32_e32 v44, 0xbfb8aa3b, v33
	v_rcp_f32_e32 v36, v36
	v_rcp_f32_e32 v37, v37
	v_exp_f32_e32 v23, v23
	v_exp_f32_e32 v44, v44
	v_and_b32_e32 v45, 0xffff0000, v22
	v_pk_mul_f32 v[24:25], v[24:25], v[36:37]
	v_add_f32_e32 v23, 1.0, v23
	v_add_f32_e32 v37, 1.0, v44
	v_lshlrev_b32_e32 v44, 16, v22
	v_rcp_f32_e32 v36, v23
	v_pk_fma_f32 v[22:23], v[42:43], v[44:45], 0 op_sel_hi:[1,1,0]
	v_rcp_f32_e32 v37, v37
	v_pk_fma_f32 v[22:23], v[46:47], v[106:107], v[22:23]
	v_mov_b32_e32 v42, v78
	v_pk_fma_f32 v[22:23], v[50:51], v[34:35], v[22:23]
	v_pk_mul_f32 v[32:33], v[32:33], v[36:37]
	v_pk_fma_f32 v[22:23], v[54:55], v[26:27], v[22:23]
	v_pk_mul_f32 v[36:37], v[32:33], v[32:33]
	v_mul_f32_e32 v26, 0xbfb8aa3b, v22
	v_mul_f32_e32 v27, 0xbfb8aa3b, v23
	v_exp_f32_e32 v26, v26
	v_exp_f32_e32 v27, v27
	v_pk_mul_f32 v[34:35], v[24:25], v[24:25]
	v_pk_mul_f32 v[104:105], v[38:39], v[38:39]
	v_add_f32_e32 v26, 1.0, v26
	v_add_f32_e32 v27, 1.0, v27
	v_rcp_f32_e32 v26, v26
	v_rcp_f32_e32 v27, v27
	v_pk_mul_f32 v[28:29], v[66:67], v[66:67]
	v_pk_mul_f32 v[22:23], v[22:23], v[26:27]
	s_nop 0
	v_pk_mul_f32 v[26:27], v[22:23], v[22:23]
	s_nop 0
	v_mov_b32_e32 v43, v26
	v_mov_b32_e32 v26, v79
	v_pk_add_f32 v[26:27], v[42:43], v[26:27]
	v_mov_b32_e32 v42, v74
	v_mov_b32_e32 v43, v36
	v_pk_add_f32 v[26:27], v[42:43], v[26:27]
	v_mov_b32_e32 v36, v75
	v_pk_add_f32 v[26:27], v[36:37], v[26:27]
	v_mov_b32_e32 v36, v108
	v_mov_b32_e32 v37, v34
	v_pk_add_f32 v[26:27], v[36:37], v[26:27]
	v_mov_b32_e32 v34, v109
	v_pk_add_f32 v[26:27], v[34:35], v[26:27]
	v_mov_b32_e32 v34, v104
	v_mov_b32_e32 v35, v28
	v_pk_add_f32 v[26:27], v[34:35], v[26:27]
	v_mov_b32_e32 v28, v105
	v_pk_add_f32 v[26:27], v[28:29], v[26:27]
	v_mov_b32_e32 v28, v87
	v_mov_b32_e32 v29, v87
	s_nop 0
	v_mov_b32_dpp v28, v26 quad_perm:[1,0,3,2] row_mask:0xf bank_mask:0xf
	v_mov_b32_dpp v29, v27 quad_perm:[1,0,3,2] row_mask:0xf bank_mask:0xf
; #define LAS __attribute__((address_space(3)))
; __device__ __forceinline__ unsigned cvt_pk_bf16(float lo, float hi) { const bf16x2_t r = __builtin_convertvector((f32x2){lo, hi}, bf16x2_t); return __builtin_bit_cast(unsigned, r); }
; __device__ __forceinline__ void gdn_prep_item(LAS unsigned char* lds, int item, int b0, PrepRaw& R, int next_item, const bf16_t* qkv, const float* bg, const float* gconv_w, unsigned char* rec, float* gtarr) {
;     ...
;             if (part < 2) {
;                 s0 = row16_sum(s0); s1 = row16_sum(s1);
;                 float sc0 = rsqrtf(s0 + EPS), sc1 = rsqrtf(s1 + EPS); if (part == 0) { sc0 *= 0.08838834764831845f; sc1 *= 0.08838834764831845f; }
; #pragma unroll
;                 for (int e = 0; e < 8; ++e) { y0[e] *= sc0; y1[e] *= sc1; }
;                 LAS unsigned char* img = lds + (part == 0 ? P2_QN : P2_KN);
;                 u32x4 w0, w1; w0.x = cvt_pk_bf16(y0[0], y0[1]); w0.y = cvt_pk_bf16(y0[2], y0[3]); w0.z = cvt_pk_bf16(y0[4], y0[5]); w0.w = cvt_pk_bf16(y0[6], y0[7]);
;                 w1.x = cvt_pk_bf16(y1[0], y1[1]); w1.y = cvt_pk_bf16(y1[2], y1[3]); w1.z = cvt_pk_bf16(y1[4], y1[5]); w1.w = cvt_pk_bf16(y1[6], y1[7]);
;                 *(LAS u32x4*)(img + (i0 * 136 + 8 * cc) * 2) = w0; *(LAS u32x4*)(img + ((i0 + 1) * 136 + 8 * cc) * 2) = w1;
;                 if (part == 1) {
;                     const float f0 = be0 * eg0, f1 = be1 * eg1;
; #pragma unroll
;                     for (int e = 0; e < 8; ++e) *(LAS unsigned*)(lds + P2_KBT + ((8 * cc + e) * 72 + i0) * 2) = cvt_pk_bf16(y0[e] * f0, y1[e] * f1);
;                 }
;             } else {
; #pragma unroll
;                 for (int e = 0; e < 8; ++e) *(LAS unsigned*)(lds + P2_VBT + ((8 * cc + e) * 72 + i0) * 2) = cvt_pk_bf16(y0[e] * be0, y1[e] * be1);
	v_pk_add_f32 v[26:27], v[26:27], v[28:29]
	v_mov_b32_e32 v28, v87
	v_mov_b32_e32 v29, v87
	s_nop 0
	v_mov_b32_dpp v28, v26 quad_perm:[2,3,0,1] row_mask:0xf bank_mask:0xf
	v_mov_b32_dpp v29, v27 quad_perm:[2,3,0,1] row_mask:0xf bank_mask:0xf
	v_pk_add_f32 v[26:27], v[26:27], v[28:29]
	v_mov_b32_e32 v28, v87
	v_mov_b32_e32 v29, v87
	s_nop 0
	v_mov_b32_dpp v28, v26 row_ror:4 row_mask:0xf bank_mask:0xf
	v_mov_b32_dpp v29, v27 row_ror:4 row_mask:0xf bank_mask:0xf
	v_pk_add_f32 v[26:27], v[26:27], v[28:29]
	v_mov_b32_e32 v28, v87
	v_mov_b32_e32 v29, v87
	s_nop 0
	v_mov_b32_dpp v28, v26 row_ror:8 row_mask:0xf bank_mask:0xf
	v_mov_b32_dpp v29, v27 row_ror:8 row_mask:0xf bank_mask:0xf
	v_pk_add_f32 v[26:27], v[26:27], v[28:29]
	s_nop 0
	v_pk_add_f32 v[26:27], v[26:27], s[0:1] op_sel_hi:[1,0]
	s_movk_i32 s0, 0x240
	v_mul_f32_e32 v28, 0x4b800000, v26
	v_cmp_gt_f32_e32 vcc, s4, v26
	s_nop 1
	v_cndmask_b32_e32 v26, v26, v28, vcc
	v_rsq_f32_e32 v26, v26
	s_nop 0
	v_mul_f32_e32 v28, 0x45800000, v26
	v_cndmask_b32_e32 v26, v26, v28, vcc
	v_mul_f32_e32 v28, 0x4b800000, v27
	v_cmp_gt_f32_e32 vcc, s4, v27
	v_pk_mul_f32 v[30:31], v[30:31], v[26:27] op_sel_hi:[1,0]
	s_nop 0
	v_cndmask_b32_e32 v27, v27, v28, vcc
	v_rsq_f32_e32 v27, v27
	s_nop 0
	v_pk_mul_f32 v[34:35], v[90:91], v[26:27] op_sel_hi:[1,0]
	v_pk_mul_f32 v[36:37], v[40:41], v[26:27] op_sel_hi:[1,0]
	v_pk_mul_f32 v[38:39], v[38:39], v[26:27] op_sel_hi:[1,0]
	v_mul_f32_e32 v26, 0x45800000, v27
	v_cndmask_b32_e32 v26, v27, v26, vcc
	v_pk_mul_f32 v[40:41], v[22:23], v[26:27] op_sel_hi:[1,0]
	v_pk_mul_f32 v[32:33], v[32:33], v[26:27] op_sel_hi:[1,0]
	v_pk_mul_f32 v[42:43], v[24:25], v[26:27] op_sel_hi:[1,0]
	v_pk_mul_f32 v[44:45], v[66:67], v[26:27] op_sel_hi:[1,0]
	v_cvt_pk_bf16_f32 v22, v40, v41
	v_cvt_pk_bf16_f32 v23, v32, v33
	v_cvt_pk_bf16_f32 v24, v42, v43
	v_cvt_pk_bf16_f32 v25, v44, v45
	v_cvt_pk_bf16_f32 v26, v30, v31
	v_cvt_pk_bf16_f32 v27, v34, v35
	v_cvt_pk_bf16_f32 v28, v36, v37
	v_cvt_pk_bf16_f32 v29, v38, v39
	ds_write_b128 v103, v[22:25] offset:17408
	ds_write_b128 v116, v[26:29] offset:17408
	s_waitcnt lgkmcnt(4)
	v_pk_mul_f32 v[22:23], v[58:59], v[60:61]
	v_mov_b32_e32 v24, v40
	v_mov_b32_e32 v25, v30
	v_pk_mul_f32 v[24:25], v[22:23], v[24:25]
	v_mov_b32_e32 v30, v41
	v_cvt_pk_bf16_f32 v26, v24, v25
	v_mad_u32_u24 v24, v1, s0, v102
	v_lshl_add_u32 v40, v24, 1, 0
	v_pk_mul_f32 v[24:25], v[22:23], v[30:31]
	v_add_u32_e32 v27, 0xd000, v40
	v_cvt_pk_bf16_f32 v24, v24, v25
	ds_write2_b32 v27, v26, v24 offset1:36
	v_mov_b32_e32 v24, v32
	v_mov_b32_e32 v25, v34
	v_pk_mul_f32 v[24:25], v[22:23], v[24:25]
	v_mov_b32_e32 v34, v33
	v_cvt_pk_bf16_f32 v26, v24, v25
	v_pk_mul_f32 v[24:25], v[22:23], v[34:35]
	s_nop 0
	v_cvt_pk_bf16_f32 v24, v24, v25
	ds_write2_b32 v27, v26, v24 offset0:72 offset1:108
	v_mov_b32_e32 v24, v42
	v_mov_b32_e32 v25, v36
	v_pk_mul_f32 v[24:25], v[22:23], v[24:25]
	v_mov_b32_e32 v36, v43
	v_cvt_pk_bf16_f32 v26, v24, v25
	v_pk_mul_f32 v[24:25], v[22:23], v[36:37]
	s_nop 0
	v_cvt_pk_bf16_f32 v24, v24, v25
	ds_write2_b32 v27, v26, v24 offset0:144 offset1:180
	v_mov_b32_e32 v24, v44
	v_mov_b32_e32 v25, v38
	v_mov_b32_e32 v38, v45
	v_pk_mul_f32 v[24:25], v[22:23], v[24:25]
	v_pk_mul_f32 v[22:23], v[22:23], v[38:39]
	v_cvt_pk_bf16_f32 v24, v24, v25
	v_cvt_pk_bf16_f32 v22, v22, v23
	ds_write2_b32 v27, v24, v22 offset0:216 offset1:252
	s_movk_i32 s0, 0x5000
	v_add_co_u32_e32 v26, vcc, s0, v88
	s_mov_b32 s0, 0x8000
	s_nop 0
	v_addc_co_u32_e32 v27, vcc, 0, v89, vcc
	v_add_co_u32_e32 v30, vcc, s0, v88
	global_load_dwordx4 v[22:25], v[62:63], off
	s_nop 0
	v_addc_co_u32_e32 v31, vcc, 0, v89, vcc
	s_mov_b32 s0, 0xb000
	global_load_dwordx4 v[26:29], v[26:27], off
	v_add_co_u32_e32 v34, vcc, s0, v88
	global_load_dwordx4 v[30:33], v[30:31], off
	s_nop 0
	v_addc_co_u32_e32 v35, vcc, 0, v89, vcc
	global_load_dwordx4 v[34:37], v[34:35], off
	s_mov_b64 s[4:5], 0x2000
	s_mov_b64 s[6:7], 0x5000
	s_mov_b64 s[8:9], 0x8000
	s_mov_b64 s[22:23], 0xb000
	v_lshl_add_u64 v[38:39], v[88:89], 0, s[4:5]
	v_lshl_add_u64 v[42:43], v[88:89], 0, s[6:7]
	v_lshl_add_u64 v[46:47], v[88:89], 0, s[8:9]
	v_lshl_add_u64 v[50:51], v[88:89], 0, s[22:23]
	v_add_u32_e32 v80, 0x8800, v40
	global_load_dwordx4 v[38:41], v[38:39], off offset:16
	s_nop 0
	global_load_dwordx4 v[42:45], v[42:43], off offset:16
	s_nop 0
	global_load_dwordx4 v[46:49], v[46:47], off offset:16
	s_nop 0
	global_load_dwordx4 v[50:53], v[50:51], off offset:16
	v_lshlrev_b32_e32 v55, 16, v10
	v_lshlrev_b32_e32 v54, 16, v2
	v_and_b32_e32 v65, 0xffff0000, v10
	v_and_b32_e32 v64, 0xffff0000, v2
	v_lshlrev_b32_e32 v57, 16, v6
	v_and_b32_e32 v67, 0xffff0000, v6
	v_mov_b32_e32 v56, v55
	v_mov_b32_e32 v66, v65
	v_lshlrev_b32_e32 v61, 16, v18
	v_and_b32_e32 v69, 0xffff0000, v18
	v_mov_b32_e32 v60, v57
	v_mov_b32_e32 v68, v67
	v_lshlrev_b32_e32 v63, 16, v14
	v_and_b32_e32 v71, 0xffff0000, v14
	v_mov_b32_e32 v62, v61
	v_mov_b32_e32 v70, v69
	v_lshlrev_b32_e32 v72, 16, v3
	v_lshlrev_b32_e32 v73, 16, v11
	v_lshlrev_b32_e32 v75, 16, v7
	v_mov_b32_e32 v74, v73
	v_lshlrev_b32_e32 v77, 16, v19
	v_mov_b32_e32 v76, v75
	v_lshlrev_b32_e32 v79, 16, v15
	v_mov_b32_e32 v78, v77
	v_and_b32_e32 v11, 0xffff0000, v11
	s_waitcnt vmcnt(7)
	v_pk_fma_f32 v[54:55], v[22:23], v[54:55], 0 op_sel_hi:[0,1,0]
	v_pk_fma_f32 v[22:23], v[22:23], v[64:65], 0 op_sel:[1,0,0] op_sel_hi:[1,1,0]
	v_pk_fma_f32 v[64:65], v[24:25], v[72:73], 0 op_sel_hi:[0,1,0]
	s_waitcnt vmcnt(6)
	v_pk_fma_f32 v[54:55], v[26:27], v[56:57], v[54:55] op_sel_hi:[0,1,1]
	v_pk_fma_f32 v[22:23], v[26:27], v[66:67], v[22:23] op_sel:[1,0,0]
	v_pk_fma_f32 v[26:27], v[28:29], v[74:75], v[64:65] op_sel_hi:[0,1,1]
	s_waitcnt vmcnt(5)
; #define LAS __attribute__((address_space(3)))
; __device__ __forceinline__ unsigned cvt_pk_bf16(float lo, float hi) { const bf16x2_t r = __builtin_convertvector((f32x2){lo, hi}, bf16x2_t); return __builtin_bit_cast(unsigned, r); }
; __device__ __forceinline__ void gdn_prep_item(LAS unsigned char* lds, int item, int b0, PrepRaw& R, int next_item, const bf16_t* qkv, const float* bg, const float* gconv_w, unsigned char* rec, float* gtarr) {
;     ...
;             } else {
; #pragma unroll
;                 for (int e = 0; e < 8; ++e) *(LAS unsigned*)(lds + P2_VBT + ((8 * cc + e) * 72 + i0) * 2) = cvt_pk_bf16(y0[e] * be0, y1[e] * be1);
;             }
;             __builtin_amdgcn_sched_barrier(0);
;         }
;     }
;     if (next_item >= 0) gdn_prep_load(R, next_item, b0, qkv, bg, tid);
;     __syncthreads();
	v_pk_fma_f32 v[54:55], v[30:31], v[60:61], v[54:55] op_sel_hi:[0,1,1]
	v_pk_fma_f32 v[22:23], v[30:31], v[68:69], v[22:23] op_sel:[1,0,0]
	v_pk_fma_f32 v[26:27], v[32:33], v[76:77], v[26:27] op_sel_hi:[0,1,1]
	s_waitcnt vmcnt(4)
	v_pk_fma_f32 v[30:31], v[34:35], v[62:63], v[54:55] op_sel_hi:[0,1,1]
	v_pk_fma_f32 v[22:23], v[34:35], v[70:71], v[22:23] op_sel:[1,0,0]
	v_mul_f32_e32 v2, 0xbfb8aa3b, v31
	v_mul_f32_e32 v6, 0xbfb8aa3b, v30
	v_mul_f32_e32 v10, 0xbfb8aa3b, v23
	v_mul_f32_e32 v14, 0xbfb8aa3b, v22
	v_exp_f32_e32 v2, v2
	v_exp_f32_e32 v6, v6
	v_exp_f32_e32 v10, v10
	v_exp_f32_e32 v14, v14
	v_add_f32_e32 v2, 1.0, v2
	v_add_f32_e32 v6, 1.0, v6
	v_add_f32_e32 v10, 1.0, v10
	v_add_f32_e32 v14, 1.0, v14
	v_rcp_f32_e32 v35, v2
	v_rcp_f32_e32 v34, v6
	v_rcp_f32_e32 v55, v10
	v_rcp_f32_e32 v54, v14
	v_pk_fma_f32 v[26:27], v[36:37], v[78:79], v[26:27] op_sel_hi:[0,1,1]
	v_mul_f32_e32 v18, 0xbfb8aa3b, v27
	v_exp_f32_e32 v2, v18
	v_mul_f32_e32 v24, 0xbfb8aa3b, v26
	v_pk_mul_f32 v[30:31], v[30:31], v[34:35]
	v_pk_mul_f32 v[22:23], v[22:23], v[54:55]
	v_exp_f32_e32 v6, v24
	v_pk_mul_f32 v[30:31], v[58:59], v[30:31]
	v_pk_mul_f32 v[22:23], v[58:59], v[22:23]
	v_cvt_pk_bf16_f32 v10, v30, v31
	v_cvt_pk_bf16_f32 v14, v22, v23
	ds_write2_b32 v80, v10, v14 offset1:36
	v_add_f32_e32 v2, 1.0, v2
	v_and_b32_e32 v10, 0xffff0000, v3
	v_mov_b32_e32 v14, v25
	v_rcp_f32_e32 v23, v2
	v_and_b32_e32 v3, 0xffff0000, v7
	v_mov_b32_e32 v2, v11
	v_pk_fma_f32 v[10:11], v[14:15], v[10:11], 0 op_sel_hi:[0,1,0]
	v_mov_b32_e32 v18, v29
	v_add_f32_e32 v22, 1.0, v6
	v_and_b32_e32 v7, 0xffff0000, v19
	v_mov_b32_e32 v6, v3
	v_pk_fma_f32 v[2:3], v[18:19], v[2:3], v[10:11] op_sel_hi:[0,1,1]
	v_mov_b32_e32 v10, v33
	v_and_b32_e32 v15, 0xffff0000, v15
	v_mov_b32_e32 v14, v7
	v_pk_fma_f32 v[2:3], v[10:11], v[6:7], v[2:3] op_sel_hi:[0,1,1]
	v_mov_b32_e32 v6, v37
	v_pk_fma_f32 v[2:3], v[6:7], v[14:15], v[2:3] op_sel_hi:[0,1,1]
	v_mul_f32_e32 v6, 0xbfb8aa3b, v3
	v_exp_f32_e32 v6, v6
	v_mul_f32_e32 v7, 0xbfb8aa3b, v2
	v_exp_f32_e32 v10, v7
	v_rcp_f32_e32 v22, v22
	v_add_f32_e32 v6, 1.0, v6
	v_rcp_f32_e32 v7, v6
	v_add_f32_e32 v6, 1.0, v10
	v_rcp_f32_e32 v6, v6
	v_pk_mul_f32 v[10:11], v[26:27], v[22:23]
	v_lshlrev_b32_e32 v15, 16, v16
	v_pk_mul_f32 v[10:11], v[58:59], v[10:11]
	v_pk_mul_f32 v[2:3], v[2:3], v[6:7]
	v_lshlrev_b32_e32 v7, 16, v8
	v_pk_mul_f32 v[2:3], v[58:59], v[2:3]
	v_cvt_pk_bf16_f32 v18, v10, v11
	v_cvt_pk_bf16_f32 v19, v2, v3
	v_lshlrev_b32_e32 v3, 16, v12
	v_lshlrev_b32_e32 v2, 16, v4
	v_mov_b32_e32 v6, v3
	s_waitcnt vmcnt(3)
	v_pk_fma_f32 v[2:3], v[38:39], v[2:3], 0 op_sel_hi:[0,1,0]
	v_lshlrev_b32_e32 v11, 16, v20
	v_mov_b32_e32 v10, v7
	s_waitcnt vmcnt(2)
	v_pk_fma_f32 v[2:3], v[42:43], v[6:7], v[2:3] op_sel_hi:[0,1,1]
	v_mov_b32_e32 v14, v11
	s_waitcnt vmcnt(1)
	v_pk_fma_f32 v[2:3], v[46:47], v[10:11], v[2:3] op_sel_hi:[0,1,1]
	s_waitcnt vmcnt(0)
	v_pk_fma_f32 v[2:3], v[50:51], v[14:15], v[2:3] op_sel_hi:[0,1,1]
	v_mul_f32_e32 v6, 0xbfb8aa3b, v3
	v_exp_f32_e32 v6, v6
	v_mul_f32_e32 v7, 0xbfb8aa3b, v2
	v_exp_f32_e32 v10, v7
	v_and_b32_e32 v11, 0xffff0000, v12
	v_add_f32_e32 v6, 1.0, v6
	v_rcp_f32_e32 v7, v6
	v_add_f32_e32 v6, 1.0, v10
	v_and_b32_e32 v10, 0xffff0000, v4
	v_and_b32_e32 v15, 0xffff0000, v8
	v_mov_b32_e32 v14, v11
	v_pk_fma_f32 v[10:11], v[38:39], v[10:11], 0 op_sel:[1,0,0] op_sel_hi:[1,1,0]
	ds_write2_b32 v80, v18, v19 offset0:72 offset1:108
	v_and_b32_e32 v19, 0xffff0000, v20
	v_mov_b32_e32 v18, v15
	v_pk_fma_f32 v[10:11], v[42:43], v[14:15], v[10:11] op_sel:[1,0,0]
	v_and_b32_e32 v23, 0xffff0000, v16
	v_mov_b32_e32 v22, v19
	v_pk_fma_f32 v[10:11], v[46:47], v[18:19], v[10:11] op_sel:[1,0,0]
	v_rcp_f32_e32 v6, v6
	v_pk_fma_f32 v[10:11], v[50:51], v[22:23], v[10:11] op_sel:[1,0,0]
	v_pk_mul_f32 v[2:3], v[2:3], v[6:7]
	v_mul_f32_e32 v4, 0xbfb8aa3b, v11
	v_exp_f32_e32 v4, v4
	v_mul_f32_e32 v8, 0xbfb8aa3b, v10
	v_exp_f32_e32 v8, v8
	v_pk_mul_f32 v[2:3], v[58:59], v[2:3]
	v_add_f32_e32 v4, 1.0, v4
	v_rcp_f32_e32 v15, v4
	v_add_f32_e32 v4, 1.0, v8
	v_rcp_f32_e32 v14, v4
	v_cvt_pk_bf16_f32 v4, v2, v3
	v_lshlrev_b32_e32 v7, 16, v9
	v_pk_mul_f32 v[2:3], v[10:11], v[14:15]
	s_nop 0
	v_pk_mul_f32 v[2:3], v[58:59], v[2:3]
	v_lshlrev_b32_e32 v11, 16, v21
	v_cvt_pk_bf16_f32 v8, v2, v3
	v_lshlrev_b32_e32 v2, 16, v5
	v_lshlrev_b32_e32 v3, 16, v13
	v_mov_b32_e32 v6, v3
	v_pk_fma_f32 v[2:3], v[40:41], v[2:3], 0 op_sel_hi:[0,1,0]
	v_mov_b32_e32 v10, v7
	v_pk_fma_f32 v[2:3], v[44:45], v[6:7], v[2:3] op_sel_hi:[0,1,1]
	v_lshlrev_b32_e32 v15, 16, v17
	v_mov_b32_e32 v14, v11
	v_pk_fma_f32 v[2:3], v[48:49], v[10:11], v[2:3] op_sel_hi:[0,1,1]
	v_pk_fma_f32 v[2:3], v[52:53], v[14:15], v[2:3] op_sel_hi:[0,1,1]
	v_mul_f32_e32 v6, 0xbfb8aa3b, v3
	v_exp_f32_e32 v6, v6
	v_mul_f32_e32 v7, 0xbfb8aa3b, v2
	v_exp_f32_e32 v10, v7
	ds_write2_b32 v80, v4, v8 offset0:144 offset1:180
	v_add_f32_e32 v4, 1.0, v6
	v_rcp_f32_e32 v7, v4
	v_add_f32_e32 v14, 1.0, v10
	v_and_b32_e32 v11, 0xffff0000, v13
	v_and_b32_e32 v10, 0xffff0000, v5
	v_mov_b32_e32 v6, v41
	v_and_b32_e32 v5, 0xffff0000, v9
	v_mov_b32_e32 v4, v11
	v_pk_fma_f32 v[10:11], v[6:7], v[10:11], 0 op_sel_hi:[0,1,0]
	v_mov_b32_e32 v6, v45
	v_and_b32_e32 v9, 0xffff0000, v21
	v_mov_b32_e32 v8, v5
	v_pk_fma_f32 v[4:5], v[6:7], v[4:5], v[10:11] op_sel_hi:[0,1,1]
	v_mov_b32_e32 v6, v49
	v_and_b32_e32 v13, 0xffff0000, v17
	v_mov_b32_e32 v12, v9
	v_pk_fma_f32 v[4:5], v[6:7], v[8:9], v[4:5] op_sel_hi:[0,1,1]
	v_mov_b32_e32 v6, v53
	v_pk_fma_f32 v[4:5], v[6:7], v[12:13], v[4:5] op_sel_hi:[0,1,1]
	v_mul_f32_e32 v6, 0xbfb8aa3b, v5
	v_exp_f32_e32 v8, v6
	v_mul_f32_e32 v6, 0xbfb8aa3b, v4
	v_exp_f32_e32 v10, v6
	v_rcp_f32_e32 v6, v14
	v_add_f32_e32 v8, 1.0, v8
	v_rcp_f32_e32 v9, v8
	v_add_f32_e32 v8, 1.0, v10
	v_rcp_f32_e32 v8, v8
	v_pk_mul_f32 v[2:3], v[2:3], v[6:7]
	s_nop 0
	v_pk_mul_f32 v[2:3], v[58:59], v[2:3]
	s_nop 0
	v_cvt_pk_bf16_f32 v6, v2, v3
	v_pk_mul_f32 v[2:3], v[4:5], v[8:9]
	s_nop 0
	v_pk_mul_f32 v[2:3], v[58:59], v[2:3]
	s_nop 0
	v_cvt_pk_bf16_f32 v2, v2, v3
	ds_write2_b32 v80, v6, v2 offset0:216 offset1:252
	s_ashr_i32 s22, s20, 1
	s_lshl_b32 s4, s22, 4
	v_or_b32_e32 v11, s4, v1
	v_mul_lo_u32 v2, v11, s1
	v_lshlrev_b32_e32 v10, 3, v86
	v_add_lshl_u32 v2, v2, v10, 1
	v_add_u32_e32 v6, 0, v2
	s_waitcnt lgkmcnt(0)
	s_barrier
; #define LAS __attribute__((address_space(3)))
; #define MFMA16(a, b, c) __builtin_amdgcn_mfma_f32_16x16x32_bf16(a, b, c, 0, 0, 0)
; __device__ __forceinline__ void gdn_prep_item(LAS unsigned char* lds, int item, int b0, PrepRaw& R, int next_item, const bf16_t* qkv, const float* bg, const float* gconv_w, unsigned char* rec, float* gtarr) {
;     ...
;     {
;         const f32x4 z4 = (f32x4){0.f, 0.f, 0.f, 0.f};
;         {
;             const int ta = wave >> 1;
; #pragma unroll
;             for (int q = 0; q < 2; ++q) { const int tb = 2 * (wave & 1) + q; f32x4 acc = z4;
; #pragma unroll
;                 for (int s = 0; s < 4; ++s) { const bf16x8 af = *(const LAS bf16x8*)(lds + P2_KN + ((16 * ta + l15) * 136 + 32 * s + 8 * g) * 2), bfr = *(const LAS bf16x8*)(lds + P2_KN + ((16 * tb + l15) * 136 + 32 * s + 8 * g) * 2);
;                     acc = MFMA16(af, bfr, acc); }
;                 const int j = 16 * tb + l15; const float Gj = Gs[j];
; #pragma unroll
;                 for (int r = 0; r < 4; ++r) { const int i = 16 * ta + 4 * g + r; Lf[i * LS + j] = (i > j) ? Bs[i] * acc[r] * __expf(Gs[i] - Gj) : 0.f; } }
;         }
;         {
;             const int rt = wave >> 1, s = wave & 1; f32x4 a0 = z4, a1 = z4;
; #pragma unroll
;             for (int ks = 0; ks < 4; ++ks) { const bf16x8 qf = *(const LAS bf16x8*)(lds + P2_QN + ((16 * rt + l15) * 136 + 32 * ks + 8 * g) * 2);
;                 const bf16x8 k0 = *(const LAS bf16x8*)(lds + P2_KN + ((32 * s + l15) * 136 + 32 * ks + 8 * g) * 2), k1 = *(const LAS bf16x8*)(lds + P2_KN + ((32 * s + 16 + l15) * 136 + 32 * ks + 8 * g) * 2);
;                 a0 = MFMA16(k0, qf, a0); a1 = MFMA16(k1, qf, a1); }
;             const int i = 16 * rt + l15; const float Gi = Gs[i];
; #pragma unroll
;             for (int r = 0; r < 4; ++r) { const int ia = 32 * s + 4 * g + r, ib = ia + 16;
;                 a0[r] = (i >= ia) ? a0[r] * __expf(Gi - Gs[ia]) : 0.f; a1[r] = (i >= ib) ? a1[r] * __expf(Gi - Gs[ib]) : 0.f; }
;             *(bf16x8*)(rec + REC_AM + ((rt * 2 + s) * 64 + lane) * 16) = pack8(a0, a1);
;         }
	s_and_b32 s23, s20, 1
	s_lshl_b32 s0, s23, 5
	v_or_b32_e32 v222, s0, v1
	v_lshl_or_b32 v223, v86, 2, s4
	v_lshl_or_b32 v230, v86, 2, s0
	v_lshlrev_b32_e32 v227, 2, v223
	v_add_u32_e32 v227, 0x1d000, v227
	v_lshlrev_b32_e32 v228, 2, v222
	v_add_u32_e32 v228, 0x1d000, v228
	v_lshlrev_b32_e32 v229, 2, v11
	v_add_u32_e32 v229, 0x1d000, v229
	v_sub_u32_e32 v225, v11, v230
	v_lshlrev_b32_e32 v230, 2, v230
	v_add_u32_e32 v230, 0x1d000, v230
	s_movk_i32 s0, 0x88
	v_mad_u32_u24 v231, v222, s0, v10
	v_lshlrev_b32_e32 v231, 1, v231
	ds_read_b128 v[200:203], v227
	ds_read_b128 v[204:207], v227 offset:256
	ds_read_b32 v216, v228
	ds_read_b32 v217, v228 offset:64
	ds_read_b32 v218, v229
	ds_read_b128 v[208:211], v230
	ds_read_b128 v[212:215], v230 offset:64
	ds_read_b128 v[136:139], v6 offset:17408
	ds_read_b128 v[152:155], v231 offset:17408
	ds_read_b128 v[168:171], v231 offset:21760
	ds_read_b128 v[184:187], v6
	ds_read_b128 v[140:143], v6 offset:17472
	ds_read_b128 v[156:159], v231 offset:17472
	ds_read_b128 v[172:175], v231 offset:21824
	ds_read_b128 v[188:191], v6 offset:64
	ds_read_b128 v[144:147], v6 offset:17536
	ds_read_b128 v[160:163], v231 offset:17536
	ds_read_b128 v[176:179], v231 offset:21888
	ds_read_b128 v[192:195], v6 offset:128
	ds_read_b128 v[148:151], v6 offset:17600
	ds_read_b128 v[164:167], v231 offset:17600
	ds_read_b128 v[180:183], v231 offset:21952
	ds_read_b128 v[196:199], v6 offset:192
	v_sub_u32_e32 v224, v223, v222
	s_movk_i32 s0, 0x110
	v_mad_u32_u24 v226, v223, s0, 0
	v_lshl_add_u32 v226, v222, 2, v226
	v_add_u32_e32 v226, 0x11800, v226
	s_waitcnt lgkmcnt(14)
	v_sub_f32_e32 v80, v200, v216
	v_sub_f32_e32 v81, v201, v216
	v_sub_f32_e32 v82, v202, v216
	v_sub_f32_e32 v83, v203, v216
	v_mul_f32_e32 v80, 0x3fb8aa3b, v80
	v_mul_f32_e32 v81, 0x3fb8aa3b, v81
	v_mul_f32_e32 v82, 0x3fb8aa3b, v82
	v_mul_f32_e32 v83, 0x3fb8aa3b, v83
	v_exp_f32_e32 v80, v80
	v_exp_f32_e32 v81, v81
	v_exp_f32_e32 v82, v82
	v_exp_f32_e32 v83, v83
	v_sub_f32_e32 v84, v200, v217
	v_sub_f32_e32 v85, v201, v217
	v_sub_f32_e32 v86, v202, v217
	v_sub_f32_e32 v87, v203, v217
	v_mul_f32_e32 v84, 0x3fb8aa3b, v84
	v_mul_f32_e32 v85, 0x3fb8aa3b, v85
	v_mul_f32_e32 v86, 0x3fb8aa3b, v86
	v_mul_f32_e32 v87, 0x3fb8aa3b, v87
	v_exp_f32_e32 v84, v84
	v_exp_f32_e32 v85, v85
	v_exp_f32_e32 v86, v86
	v_exp_f32_e32 v87, v87
	v_sub_f32_e32 v88, v218, v208
	v_sub_f32_e32 v89, v218, v209
	v_sub_f32_e32 v90, v218, v210
	v_sub_f32_e32 v91, v218, v211
	v_mul_f32_e32 v88, 0x3fb8aa3b, v88
	v_mul_f32_e32 v89, 0x3fb8aa3b, v89
	v_mul_f32_e32 v90, 0x3fb8aa3b, v90
	v_mul_f32_e32 v91, 0x3fb8aa3b, v91
	v_exp_f32_e32 v88, v88
	v_exp_f32_e32 v89, v89
	v_exp_f32_e32 v90, v90
	v_exp_f32_e32 v91, v91
	v_sub_f32_e32 v92, v218, v212
	v_sub_f32_e32 v93, v218, v213
	v_sub_f32_e32 v94, v218, v214
	v_sub_f32_e32 v95, v218, v215
	v_mul_f32_e32 v92, 0x3fb8aa3b, v92
	v_mul_f32_e32 v93, 0x3fb8aa3b, v93
	v_mul_f32_e32 v94, 0x3fb8aa3b, v94
	v_mul_f32_e32 v95, 0x3fb8aa3b, v95
	v_exp_f32_e32 v92, v92
	v_exp_f32_e32 v93, v93
	v_exp_f32_e32 v94, v94
	v_exp_f32_e32 v95, v95
	s_waitcnt lgkmcnt(12)
	v_mfma_f32_16x16x32_bf16 v[64:67], v[136:139], v[152:155], 0
	v_mfma_f32_16x16x32_bf16 v[68:71], v[136:139], v[168:171], 0
	v_mfma_f32_16x16x32_bf16 v[72:75], v[152:155], v[184:187], 0
	v_mfma_f32_16x16x32_bf16 v[76:79], v[168:171], v[184:187], 0
	s_waitcnt lgkmcnt(8)
	v_mfma_f32_16x16x32_bf16 v[64:67], v[140:143], v[156:159], v[64:67]
	v_mfma_f32_16x16x32_bf16 v[68:71], v[140:143], v[172:175], v[68:71]
	v_mfma_f32_16x16x32_bf16 v[72:75], v[156:159], v[188:191], v[72:75]
	v_mfma_f32_16x16x32_bf16 v[76:79], v[172:175], v[188:191], v[76:79]
	s_waitcnt lgkmcnt(4)
	v_mfma_f32_16x16x32_bf16 v[64:67], v[144:147], v[160:163], v[64:67]
	v_mfma_f32_16x16x32_bf16 v[68:71], v[144:147], v[176:179], v[68:71]
	v_mfma_f32_16x16x32_bf16 v[72:75], v[160:163], v[192:195], v[72:75]
	v_mfma_f32_16x16x32_bf16 v[76:79], v[176:179], v[192:195], v[76:79]
	s_waitcnt lgkmcnt(0)
	v_mfma_f32_16x16x32_bf16 v[64:67], v[148:151], v[164:167], v[64:67]
	v_mfma_f32_16x16x32_bf16 v[68:71], v[148:151], v[180:183], v[68:71]
	v_mfma_f32_16x16x32_bf16 v[72:75], v[164:167], v[196:199], v[72:75]
	v_mfma_f32_16x16x32_bf16 v[76:79], v[180:183], v[196:199], v[76:79]
	v_cmp_lt_i32_e64 s[36:37], 0, v224
	v_cmp_lt_i32_e64 s[38:39], -1, v224
	v_cmp_lt_i32_e64 s[40:41], -2, v224
	v_cmp_lt_i32_e64 s[42:43], -3, v224
	s_nop 3
	v_mul_f32_e32 v119, v64, v204
	v_mul_f32_e32 v120, v65, v205
	v_mul_f32_e32 v121, v66, v206
	v_mul_f32_e32 v122, v67, v207
	v_mul_f32_e32 v119, v119, v80
	v_mul_f32_e32 v120, v120, v81
	v_mul_f32_e32 v121, v121, v82
	v_mul_f32_e32 v122, v122, v83
	v_cndmask_b32_e64 v119, 0, v119, s[36:37]
	v_cndmask_b32_e64 v120, 0, v120, s[38:39]
	v_cndmask_b32_e64 v121, 0, v121, s[40:41]
	v_cndmask_b32_e64 v122, 0, v122, s[42:43]
	ds_write_b32 v226, v119
	ds_write_b32 v226, v120 offset:272
	ds_write_b32 v226, v121 offset:544
	ds_write_b32 v226, v122 offset:816
	v_cmp_lt_i32_e64 s[36:37], 16, v224
	v_cmp_lt_i32_e64 s[38:39], 15, v224
	v_cmp_lt_i32_e64 s[40:41], 14, v224
	v_cmp_lt_i32_e64 s[42:43], 13, v224
	v_mul_f32_e32 v119, v68, v204
	v_mul_f32_e32 v120, v69, v205
	v_mul_f32_e32 v121, v70, v206
	v_mul_f32_e32 v122, v71, v207
	v_mul_f32_e32 v119, v119, v84
	v_mul_f32_e32 v120, v120, v85
	v_mul_f32_e32 v121, v121, v86
	v_mul_f32_e32 v122, v122, v87
	v_cndmask_b32_e64 v119, 0, v119, s[36:37]
	v_cndmask_b32_e64 v120, 0, v120, s[38:39]
	v_cndmask_b32_e64 v121, 0, v121, s[40:41]
	v_cndmask_b32_e64 v122, 0, v122, s[42:43]
	ds_write_b32 v226, v119 offset:64
	ds_write_b32 v226, v120 offset:336
	ds_write_b32 v226, v121 offset:608
	ds_write_b32 v226, v122 offset:880
; #define LAS __attribute__((address_space(3)))
; __device__ __forceinline__ void gdn_prep_item(LAS unsigned char* lds, int item, int b0, PrepRaw& R, int next_item, const bf16_t* qkv, const float* bg, const float* gconv_w, unsigned char* rec, float* gtarr) {
;     ...
;             const int i = 16 * rt + l15; const float Gi = Gs[i];
; #pragma unroll
;             for (int r = 0; r < 4; ++r) { const int ia = 32 * s + 4 * g + r, ib = ia + 16;
;                 a0[r] = (i >= ia) ? a0[r] * __expf(Gi - Gs[ia]) : 0.f; a1[r] = (i >= ib) ? a1[r] * __expf(Gi - Gs[ib]) : 0.f; }
;             *(bf16x8*)(rec + REC_AM + ((rt * 2 + s) * 64 + lane) * 16) = pack8(a0, a1);
;         }
;     }
;     __syncthreads();
;     if (tid < 64) { const int blk = tid >> 4, cidx = tid & 15; float x[16];
; #pragma unroll
;         for (int i = 0; i < 16; ++i) x[i] = (i == cidx) ? 1.f : 0.f;
; #pragma unroll
;         for (int i = 1; i < 16; ++i) { float a = 0.f; const LAS float* row = Lf + (16 * blk + i) * LS + 16 * blk;
; #pragma unroll
;             for (int j4 = 0; j4 < (i + 3) / 4; ++j4) { const f32x4 l4 = *(const LAS f32x4*)(row + 4 * j4);
; #pragma unroll
;                 for (int e = 0; e < 4; ++e) if (4 * j4 + e < i) a += l4[e] * x[4 * j4 + e]; }
;             if (i > cidx) x[i] = -a; }
; #pragma unroll
;         for (int i = 0; i < 16; ++i) Tf[(16 * blk + i) * LS + 16 * blk + cidx] = x[i];
;     }
	v_cmp_le_i32_e64 s[36:37], 0, v225
	v_cmp_le_i32_e64 s[38:39], 1, v225
	v_cmp_le_i32_e64 s[40:41], 2, v225
	v_cmp_le_i32_e64 s[42:43], 3, v225
	v_mul_f32_e32 v72, v72, v88
	v_mul_f32_e32 v73, v73, v89
	v_mul_f32_e32 v74, v74, v90
	v_mul_f32_e32 v75, v75, v91
	v_cndmask_b32_e64 v72, 0, v72, s[36:37]
	v_cndmask_b32_e64 v73, 0, v73, s[38:39]
	v_cndmask_b32_e64 v74, 0, v74, s[40:41]
	v_cndmask_b32_e64 v75, 0, v75, s[42:43]
	v_cvt_pk_bf16_f32 v232, v72, v73
	v_cvt_pk_bf16_f32 v233, v74, v75
	v_cmp_le_i32_e64 s[36:37], 16, v225
	v_cmp_le_i32_e64 s[38:39], 17, v225
	v_cmp_le_i32_e64 s[40:41], 18, v225
	v_cmp_le_i32_e64 s[42:43], 19, v225
	v_mul_f32_e32 v76, v76, v92
	v_mul_f32_e32 v77, v77, v93
	v_mul_f32_e32 v78, v78, v94
	v_mul_f32_e32 v79, v79, v95
	v_cndmask_b32_e64 v76, 0, v76, s[36:37]
	v_cndmask_b32_e64 v77, 0, v77, s[38:39]
	v_cndmask_b32_e64 v78, 0, v78, s[40:41]
	v_cndmask_b32_e64 v79, 0, v79, s[42:43]
	v_cvt_pk_bf16_f32 v234, v76, v77
	v_cvt_pk_bf16_f32 v235, v78, v79
	s_add_i32 s0, s18, 0xfffff9c8
	s_cmpk_lt_i32 s18, 0x638
	s_cselect_b32 s0, s18, s0
	s_cselect_b32 s1, s19, 0
	v_readlane_b32 s36, v245, 19
	v_readlane_b32 s48, v245, 31
	v_readlane_b32 s49, v245, 32
	s_mul_i32 s1, s1, 0x12000
	s_mul_hi_u32 s6, s0, 0x12000
	s_cselect_b32 s5, s64, s49
	s_cselect_b32 s4, s33, s48
	s_add_i32 s6, s6, s1
	s_mul_i32 s0, s0, 0x12000
	v_lshlrev_b32_e32 v7, 4, v101
	s_add_u32 s4, s4, s0
	s_waitcnt lgkmcnt(0)
	v_lshl_or_b32 v2, s20, 10, v7
	s_addc_u32 s5, s5, s6
	v_ashrrev_i32_e32 v3, 31, v2
	v_lshl_add_u64 v[2:3], s[4:5], 0, v[2:3]
	v_add_co_u32_e32 v2, vcc, 0xc000, v2
	v_readlane_b32 s37, v245, 20
	s_nop 0
	v_addc_co_u32_e32 v3, vcc, 0, v3, vcc
	v_cmp_gt_i32_e32 vcc, 64, v99
	v_readlane_b32 s38, v245, 21
	v_readlane_b32 s39, v245, 22
	v_readlane_b32 s40, v245, 23
	v_readlane_b32 s41, v245, 24
	v_readlane_b32 s42, v245, 25
	v_readlane_b32 s43, v245, 26
	v_readlane_b32 s44, v245, 27
	v_readlane_b32 s45, v245, 28
	v_readlane_b32 s46, v245, 29
	v_readlane_b32 s47, v245, 30
	v_readlane_b32 s50, v245, 33
	v_readlane_b32 s51, v245, 34
	global_store_dwordx4 v[2:3], v[232:235], off sc0 sc1
	s_barrier
	s_and_saveexec_b64 s[6:7], vcc
	s_cbranch_execz .LBB0_689
	v_and_b32_e32 v61, -16, v99
	v_lshlrev_b32_e32 v96, 8, v61
	v_lshl_add_u32 v96, v61, 4, v96
	v_lshl_add_u32 v96, v61, 2, v96
	v_add_u32_e32 v97, 0x11800, v96
	v_lshl_add_u32 v119, v1, 2, v96
	v_add_u32_e32 v119, 0x15c00, v119
	v_cmp_eq_u32_e32 vcc, 0, v1
	s_nop 1
	v_cndmask_b32_e64 v248, 0, 1.0, vcc
	ds_read_b128 v[136:139], v97 offset:272
	ds_read_b128 v[140:143], v97 offset:544
	ds_read_b128 v[144:147], v97 offset:816
	ds_read_b128 v[148:151], v97 offset:1088
	ds_read_b128 v[152:155], v97 offset:1360
	ds_read_b128 v[156:159], v97 offset:1376
	ds_read_b128 v[160:163], v97 offset:1632
	ds_read_b128 v[164:167], v97 offset:1648
	ds_read_b128 v[168:171], v97 offset:1904
	ds_read_b128 v[172:175], v97 offset:1920
	ds_read_b128 v[176:179], v97 offset:2176
	ds_read_b128 v[180:183], v97 offset:2192
	ds_read_b128 v[184:187], v97 offset:2448
	ds_read_b128 v[188:191], v97 offset:2464
	s_waitcnt lgkmcnt(13)
	v_cmp_eq_u32_e64 s[0:1], 1, v1
	v_cmp_gt_u32_e32 vcc, 1, v1
	v_fma_f32 v132, v248, v136, 0
	s_nop 1
	v_cndmask_b32_e64 v249, 0, 1.0, s[0:1]
	v_cndmask_b32_e64 v249, v249, -v132, vcc
	ds_read_b128 v[192:195], v97 offset:2480
	s_waitcnt lgkmcnt(13)
	v_cmp_eq_u32_e64 s[0:1], 2, v1
	v_cmp_gt_u32_e32 vcc, 2, v1
	v_fma_f32 v133, v248, v140, 0
	v_fmac_f32_e32 v133, v141, v249
	s_nop 1
	v_cndmask_b32_e64 v250, 0, 1.0, s[0:1]
	v_cndmask_b32_e64 v250, v250, -v133, vcc
	ds_read_b128 v[196:199], v97 offset:2720
	s_waitcnt lgkmcnt(13)
	v_cmp_eq_u32_e64 s[0:1], 3, v1
	v_cmp_gt_u32_e32 vcc, 3, v1
	v_fma_f32 v132, v248, v144, 0
	v_fmac_f32_e32 v132, v145, v249
	v_fmac_f32_e32 v132, v146, v250
	v_cndmask_b32_e64 v251, 0, 1.0, s[0:1]
	v_cndmask_b32_e64 v251, v251, -v132, vcc
	ds_read_b128 v[200:203], v97 offset:2736
	s_waitcnt lgkmcnt(13)
	v_cmp_eq_u32_e64 s[0:1], 4, v1
	v_cmp_gt_u32_e32 vcc, 4, v1
	v_fma_f32 v133, v248, v148, 0
	v_fmac_f32_e32 v133, v149, v249
	v_fmac_f32_e32 v133, v150, v250
	v_fmac_f32_e32 v133, v151, v251
	v_cndmask_b32_e64 v252, 0, 1.0, s[0:1]
	v_cndmask_b32_e64 v252, v252, -v133, vcc
	ds_read_b128 v[204:207], v97 offset:2752
	s_waitcnt lgkmcnt(13)
	v_cmp_eq_u32_e64 s[0:1], 5, v1
	v_cmp_gt_u32_e32 vcc, 5, v1
	v_fma_f32 v132, v248, v152, 0
	v_fmac_f32_e32 v132, v153, v249
	v_fmac_f32_e32 v132, v154, v250
	v_fmac_f32_e32 v132, v155, v251
	ds_read_b128 v[208:211], v97 offset:2992
	s_waitcnt lgkmcnt(13)
	v_fmac_f32_e32 v132, v156, v252
	v_cndmask_b32_e64 v253, 0, 1.0, s[0:1]
	v_cndmask_b32_e64 v253, v253, -v132, vcc
	ds_read_b128 v[212:215], v97 offset:3008
	s_waitcnt lgkmcnt(13)
	v_cmp_eq_u32_e64 s[0:1], 6, v1
	v_cmp_gt_u32_e32 vcc, 6, v1
	v_fma_f32 v133, v248, v160, 0
	v_fmac_f32_e32 v133, v161, v249
	v_fmac_f32_e32 v133, v162, v250
	v_fmac_f32_e32 v133, v163, v251
	ds_read_b128 v[216:219], v97 offset:3024
	s_waitcnt lgkmcnt(13)
	v_fmac_f32_e32 v133, v164, v252
	v_fmac_f32_e32 v133, v165, v253
	v_cndmask_b32_e64 v254, 0, 1.0, s[0:1]
	v_cndmask_b32_e64 v254, v254, -v133, vcc
	ds_read_b128 v[64:67], v97 offset:3264
	s_waitcnt lgkmcnt(13)
	v_cmp_eq_u32_e64 s[0:1], 7, v1
	v_cmp_gt_u32_e32 vcc, 7, v1
	v_fma_f32 v132, v248, v168, 0
	v_fmac_f32_e32 v132, v169, v249
	v_fmac_f32_e32 v132, v170, v250
	v_fmac_f32_e32 v132, v171, v251
	ds_read_b128 v[68:71], v97 offset:3280
	s_waitcnt lgkmcnt(13)
	v_fmac_f32_e32 v132, v172, v252
	v_fmac_f32_e32 v132, v173, v253
	v_fmac_f32_e32 v132, v174, v254
	v_cndmask_b32_e64 v255, 0, 1.0, s[0:1]
	v_cndmask_b32_e64 v255, v255, -v132, vcc
	ds_read_b128 v[72:75], v97 offset:3296
	s_waitcnt lgkmcnt(13)
; #define LAS __attribute__((address_space(3)))
; __device__ __forceinline__ void gdn_prep_item(LAS unsigned char* lds, int item, int b0, PrepRaw& R, int next_item, const bf16_t* qkv, const float* bg, const float* gconv_w, unsigned char* rec, float* gtarr) {
;     ...
;     if (tid < 64) { const int blk = tid >> 4, cidx = tid & 15; float x[16];
; #pragma unroll
;         for (int i = 0; i < 16; ++i) x[i] = (i == cidx) ? 1.f : 0.f;
; #pragma unroll
;         for (int i = 1; i < 16; ++i) { float a = 0.f; const LAS float* row = Lf + (16 * blk + i) * LS + 16 * blk;
; #pragma unroll
;             for (int j4 = 0; j4 < (i + 3) / 4; ++j4) { const f32x4 l4 = *(const LAS f32x4*)(row + 4 * j4);
; #pragma unroll
;                 for (int e = 0; e < 4; ++e) if (4 * j4 + e < i) a += l4[e] * x[4 * j4 + e]; }
;             if (i > cidx) x[i] = -a; }
; #pragma unroll
;         for (int i = 0; i < 16; ++i) Tf[(16 * blk + i) * LS + 16 * blk + cidx] = x[i];
;     }
	v_cmp_eq_u32_e64 s[0:1], 8, v1
	v_cmp_gt_u32_e32 vcc, 8, v1
	v_fma_f32 v133, v248, v176, 0
	v_fmac_f32_e32 v133, v177, v249
	v_fmac_f32_e32 v133, v178, v250
	v_fmac_f32_e32 v133, v179, v251
	ds_read_b128 v[76:79], v97 offset:3536
	s_waitcnt lgkmcnt(13)
	v_fmac_f32_e32 v133, v180, v252
	v_fmac_f32_e32 v133, v181, v253
	v_fmac_f32_e32 v133, v182, v254
	v_fmac_f32_e32 v133, v183, v255
	v_cndmask_b32_e64 v240, 0, 1.0, s[0:1]
	v_cndmask_b32_e64 v240, v240, -v133, vcc
	ds_read_b128 v[80:83], v97 offset:3552
	s_waitcnt lgkmcnt(13)
	v_cmp_eq_u32_e64 s[0:1], 9, v1
	v_cmp_gt_u32_e32 vcc, 9, v1
	v_fma_f32 v132, v248, v184, 0
	v_fmac_f32_e32 v132, v185, v249
	v_fmac_f32_e32 v132, v186, v250
	v_fmac_f32_e32 v132, v187, v251
	ds_read_b128 v[84:87], v97 offset:3568
	s_waitcnt lgkmcnt(13)
	v_fmac_f32_e32 v132, v188, v252
	v_fmac_f32_e32 v132, v189, v253
	v_fmac_f32_e32 v132, v190, v254
	v_fmac_f32_e32 v132, v191, v255
	ds_read_b128 v[88:91], v97 offset:3584
	s_waitcnt lgkmcnt(13)
	v_fmac_f32_e32 v132, v192, v240
	v_cndmask_b32_e64 v241, 0, 1.0, s[0:1]
	v_cndmask_b32_e64 v241, v241, -v132, vcc
	ds_read_b128 v[92:95], v97 offset:3808
	s_waitcnt lgkmcnt(13)
	v_cmp_eq_u32_e64 s[0:1], 10, v1
	v_cmp_gt_u32_e32 vcc, 10, v1
	v_fma_f32 v133, v248, v196, 0
	v_fmac_f32_e32 v133, v197, v249
	v_fmac_f32_e32 v133, v198, v250
	v_fmac_f32_e32 v133, v199, v251
	ds_read_b128 v[120:123], v97 offset:3824
	s_waitcnt lgkmcnt(13)
	v_fmac_f32_e32 v133, v200, v252
	v_fmac_f32_e32 v133, v201, v253
	v_fmac_f32_e32 v133, v202, v254
	v_fmac_f32_e32 v133, v203, v255
	ds_read_b128 v[124:127], v97 offset:3840
	s_waitcnt lgkmcnt(13)
	v_fmac_f32_e32 v133, v204, v240
	v_fmac_f32_e32 v133, v205, v241
	v_cndmask_b32_e64 v242, 0, 1.0, s[0:1]
	v_cndmask_b32_e64 v242, v242, -v133, vcc
	ds_read_b128 v[128:131], v97 offset:3856
	s_waitcnt lgkmcnt(13)
	v_cmp_eq_u32_e64 s[0:1], 11, v1
	v_cmp_gt_u32_e32 vcc, 11, v1
	v_fma_f32 v132, v248, v208, 0
	v_fmac_f32_e32 v132, v209, v249
	v_fmac_f32_e32 v132, v210, v250
	v_fmac_f32_e32 v132, v211, v251
	ds_read_b128 v[222:225], v97 offset:4080
	s_waitcnt lgkmcnt(13)
	v_fmac_f32_e32 v132, v212, v252
	v_fmac_f32_e32 v132, v213, v253
	v_fmac_f32_e32 v132, v214, v254
	v_fmac_f32_e32 v132, v215, v255
	ds_read_b128 v[226:229], v97 offset:4096
	s_waitcnt lgkmcnt(13)
	v_fmac_f32_e32 v132, v216, v240
	v_fmac_f32_e32 v132, v217, v241
	v_fmac_f32_e32 v132, v218, v242
	v_cndmask_b32_e64 v243, 0, 1.0, s[0:1]
	v_cndmask_b32_e64 v243, v243, -v132, vcc
	ds_read_b128 v[230:233], v97 offset:4112
	s_waitcnt lgkmcnt(13)
	v_cmp_eq_u32_e64 s[0:1], 12, v1
	v_cmp_gt_u32_e32 vcc, 12, v1
	v_fma_f32 v133, v248, v64, 0
	v_fmac_f32_e32 v133, v65, v249
	v_fmac_f32_e32 v133, v66, v250
	v_fmac_f32_e32 v133, v67, v251
	ds_read_b128 v[234:237], v97 offset:4128
	s_waitcnt lgkmcnt(13)
	v_fmac_f32_e32 v133, v68, v252
	v_fmac_f32_e32 v133, v69, v253
	v_fmac_f32_e32 v133, v70, v254
	v_fmac_f32_e32 v133, v71, v255
	s_waitcnt lgkmcnt(12)
	v_fmac_f32_e32 v133, v72, v240
	v_fmac_f32_e32 v133, v73, v241
	v_fmac_f32_e32 v133, v74, v242
	v_fmac_f32_e32 v133, v75, v243
	v_cndmask_b32_e64 v102, 0, 1.0, s[0:1]
	v_cndmask_b32_e64 v102, v102, -v133, vcc
	s_waitcnt lgkmcnt(11)
	v_cmp_eq_u32_e64 s[0:1], 13, v1
	v_cmp_gt_u32_e32 vcc, 13, v1
	v_fma_f32 v132, v248, v76, 0
	v_fmac_f32_e32 v132, v77, v249
	v_fmac_f32_e32 v132, v78, v250
	v_fmac_f32_e32 v132, v79, v251
	s_waitcnt lgkmcnt(10)
	v_fmac_f32_e32 v132, v80, v252
	v_fmac_f32_e32 v132, v81, v253
	v_fmac_f32_e32 v132, v82, v254
	v_fmac_f32_e32 v132, v83, v255
	s_waitcnt lgkmcnt(9)
	v_fmac_f32_e32 v132, v84, v240
	v_fmac_f32_e32 v132, v85, v241
	v_fmac_f32_e32 v132, v86, v242
	v_fmac_f32_e32 v132, v87, v243
	s_waitcnt lgkmcnt(8)
	v_fmac_f32_e32 v132, v88, v102
	v_cndmask_b32_e64 v103, 0, 1.0, s[0:1]
	v_cndmask_b32_e64 v103, v103, -v132, vcc
	s_waitcnt lgkmcnt(7)
	v_cmp_eq_u32_e64 s[0:1], 14, v1
	v_cmp_gt_u32_e32 vcc, 14, v1
	v_fma_f32 v133, v248, v92, 0
	v_fmac_f32_e32 v133, v93, v249
	v_fmac_f32_e32 v133, v94, v250
	v_fmac_f32_e32 v133, v95, v251
	s_waitcnt lgkmcnt(6)
	v_fmac_f32_e32 v133, v120, v252
	v_fmac_f32_e32 v133, v121, v253
	v_fmac_f32_e32 v133, v122, v254
	v_fmac_f32_e32 v133, v123, v255
	s_waitcnt lgkmcnt(5)
	v_fmac_f32_e32 v133, v124, v240
	v_fmac_f32_e32 v133, v125, v241
	v_fmac_f32_e32 v133, v126, v242
	v_fmac_f32_e32 v133, v127, v243
	s_waitcnt lgkmcnt(4)
	v_fmac_f32_e32 v133, v128, v102
	v_fmac_f32_e32 v133, v129, v103
	v_cndmask_b32_e64 v104, 0, 1.0, s[0:1]
	v_cndmask_b32_e64 v104, v104, -v133, vcc
	s_waitcnt lgkmcnt(3)
	v_cmp_eq_u32_e64 s[0:1], 15, v1
	v_cmp_gt_u32_e32 vcc, 15, v1
	v_fma_f32 v132, v248, v222, 0
	v_fmac_f32_e32 v132, v223, v249
	v_fmac_f32_e32 v132, v224, v250
	v_fmac_f32_e32 v132, v225, v251
	s_waitcnt lgkmcnt(2)
	v_fmac_f32_e32 v132, v226, v252
	v_fmac_f32_e32 v132, v227, v253
	v_fmac_f32_e32 v132, v228, v254
	v_fmac_f32_e32 v132, v229, v255
	s_waitcnt lgkmcnt(1)
	v_fmac_f32_e32 v132, v230, v240
	v_fmac_f32_e32 v132, v231, v241
	v_fmac_f32_e32 v132, v232, v242
	v_fmac_f32_e32 v132, v233, v243
	s_waitcnt lgkmcnt(0)
	v_fmac_f32_e32 v132, v234, v102
	v_fmac_f32_e32 v132, v235, v103
	v_fmac_f32_e32 v132, v236, v104
	v_cndmask_b32_e64 v105, 0, 1.0, s[0:1]
	v_cndmask_b32_e64 v105, v105, -v132, vcc
	ds_write_b32 v119, v248
	ds_write_b32 v119, v249 offset:272
	ds_write_b32 v119, v250 offset:544
	ds_write_b32 v119, v251 offset:816
	ds_write_b32 v119, v252 offset:1088
	ds_write_b32 v119, v253 offset:1360
	ds_write_b32 v119, v254 offset:1632
	ds_write_b32 v119, v255 offset:1904
	ds_write_b32 v119, v240 offset:2176
	ds_write_b32 v119, v241 offset:2448
	ds_write_b32 v119, v242 offset:2720
	ds_write_b32 v119, v243 offset:2992
	ds_write_b32 v119, v102 offset:3264
	ds_write_b32 v119, v103 offset:3536
	ds_write_b32 v119, v104 offset:3808
	ds_write_b32 v119, v105 offset:4080

; __device__ __forceinline__ int fresh_tid() { int t = threadIdx.x; asm volatile("" : "+v"(t)); return t; }
; __device__ __forceinline__ void gdn_all(LAS unsigned char* lds, const XcdBarrier& xbar, const int G, const int bx, unsigned char* ws, float* out, const bf16_t* qkv, const float* bg, const float* gconv_w, ...
;     ...
;     if (nlate > 0 && bx >= G - nlate) {
;         const int item = nfull * G + (bx - (G - nlate)); PrepRaw R; gdn_prep_load(R, item, 0, qkv, bg, fresh_tid());
;         gdn_prep_item(lds, item, 0, R, -1, qkv, bg, gconv_w, gdn_rec(ws, out, item), gtarr);
;         asm volatile("s_waitcnt vmcnt(0)" ::: "memory"); __syncthreads();
;         if (threadIdx.x == 0) { __builtin_amdgcn_fence(__ATOMIC_RELEASE, "agent"); asm volatile("s_waitcnt vmcnt(0)" ::: "memory"); __hip_atomic_fetch_add(late_cnt, 1u, __ATOMIC_RELAXED, __HIP_MEMORY_SCOPE_AGENT); }
;     }
.LBB0_703:
	s_or_b64 exec, exec, s[0:1]
	s_add_i32 s99, s99, 1
	s_cmp_lt_u32 s99, 3
	s_cbranch_scc1 .Llt_loop

; template <class RecFn>
; __device__ __forceinline__ void gdn_scan(LAS unsigned char* lds, int bh, int b0, RecFn rec_of, const float* gtarr, bf16_t* zb, const float* gnorm_w, float* Sout, const unsigned* late_cnt, unsigned late_need, int cwait) {
;     ...
;     auto late_wait = [&]() {
;         if (threadIdx.x == 0) { unsigned polls = 0;
;             while (__hip_atomic_load(late_cnt, __ATOMIC_RELAXED, __HIP_MEMORY_SCOPE_AGENT) < late_need) { if (++polls > (1u << 20)) break; __builtin_amdgcn_s_sleep(8); }
;             __builtin_amdgcn_fence(__ATOMIC_ACQUIRE, "agent"); asm volatile("s_waitcnt vmcnt(0)" ::: "memory"); }
;         __syncthreads(); };
;     if (cwait == 0) late_wait();
; __device__ __forceinline__ void gdn_all(LAS unsigned char* lds, const XcdBarrier& xbar, const int G, const int bx, unsigned char* ws, float* out, const bf16_t* qkv, const float* bg, const float* gconv_w, ...
;     ...
;         if (bx < 64) { const int cw = nfull * G / 8 - (bx >> 3) * NCHUNK;
;             gdn_scan(lds, bx, 0, rec_of, gtarr, zb, gnorm_w, out + O_PREC + (size_t)bx * DK * DV, late_cnt, (unsigned)nlate, nlate > 0 ? (cw < 0 ? 0 : cw) : NCHUNK + 1); }
.LBB0_741:
	s_or_b64 exec, exec, s[0:1]
	s_ashr_i32 s0, s3, 31
	s_lshr_b32 s0, s0, 29
	s_add_i32 s3, s3, s0
	s_ashr_i32 s24, s94, 3
	s_ashr_i32 s0, s3, 3
	s_mul_i32 s1, s24, 0xffffffdf
	s_add_i32 s0, s0, s1
	s_max_i32 s3, s0, 0
	s_and_b64 s[0:1], exec, s[16:17]
	s_cselect_b32 s3, s3, 34
	s_mov_b32 s3, 24
	s_mov_b32 s2, 0xc0
	s_cmp_lg_u32 s3, 0
	s_cbranch_scc1 .LBB0_758
	s_and_saveexec_b64 s[0:1], s[66:67]
	s_cbranch_execz .LBB0_757
	v_mov_b32_e32 v1, 0
	global_load_dword v3, v1, s[14:15] sc1
	s_waitcnt vmcnt(0)
	v_cmp_le_u32_e32 vcc, s2, v3
	s_cbranch_vccnz .LBB0_756
	s_mov_b32 s6, 0x100008
	s_branch .LBB0_747

; template <class RecFn>
; __device__ __forceinline__ void gdn_scan(LAS unsigned char* lds, int bh, int b0, RecFn rec_of, const float* gtarr, bf16_t* zb, const float* gnorm_w, float* Sout, const unsigned* late_cnt, unsigned late_need, int cwait) {
;     ...
;     auto late_wait = [&]() {
;         if (threadIdx.x == 0) { unsigned polls = 0;
;             while (__hip_atomic_load(late_cnt, __ATOMIC_RELAXED, __HIP_MEMORY_SCOPE_AGENT) < late_need) { if (++polls > (1u << 20)) break; __builtin_amdgcn_s_sleep(8); }
;             __builtin_amdgcn_fence(__ATOMIC_ACQUIRE, "agent"); asm volatile("s_waitcnt vmcnt(0)" ::: "memory"); }
;         __syncthreads(); };
;     ...
; #pragma unroll 1
;     for (int c = 0; c < NCHUNK; ++c) {
;         if (c + 1 == cwait) late_wait();
.LBB0_779:
	s_or_b64 exec, exec, s[22:23]
	s_barrier
	s_add_i32 s3, s3, 3
	s_add_u32 s14, s14, 4
	s_addc_u32 s15, s15, 0
	s_cmpk_gt_u32 s3, 0x20
	s_cselect_b32 s3, 0x63, s3
